# dwconv: interior-unit fast loop body (scalar row addressing, no range masks) with next-unit row prefetch
# speedup vs baseline: 1.0009x; 1.0009x over previous
.Ldw_fast:
	v_readlane_b32 s3, v255, 22
	s_mov_b32 s96, s70
	s_mov_b32 s97, s84
	s_cmp_lg_u32 s3, 0
	s_cbranch_scc1 .Ldw_have
	s_add_i32 s4, s2, -15
	s_ashr_i32 s5, s4, 31
	s_lshl_b64 s[4:5], s[4:5], 11
	v_lshl_add_u64 v[174:175], v[114:115], 0, s[4:5]
	global_load_dword v206, v[174:175], off
	global_load_dword v207, v[174:175], off offset:2048
	s_add_u32 s4, s4, 0x1000
	s_addc_u32 s5, s5, 0
	v_lshl_add_u64 v[176:177], v[114:115], 0, s[4:5]
	global_load_dword v208, v[176:177], off
	global_load_dword v209, v[176:177], off offset:2048
	s_add_u32 s4, s4, 0x1000
	s_addc_u32 s5, s5, 0
	v_lshl_add_u64 v[174:175], v[114:115], 0, s[4:5]
	global_load_dword v210, v[174:175], off
	global_load_dword v211, v[174:175], off offset:2048
	s_add_u32 s4, s4, 0x1000
	s_addc_u32 s5, s5, 0
	v_lshl_add_u64 v[176:177], v[114:115], 0, s[4:5]
	global_load_dword v212, v[176:177], off
	global_load_dword v213, v[176:177], off offset:2048
	s_add_u32 s4, s4, 0x1000
	s_addc_u32 s5, s5, 0
	v_lshl_add_u64 v[174:175], v[114:115], 0, s[4:5]
	global_load_dword v214, v[174:175], off
	global_load_dword v215, v[174:175], off offset:2048
	s_add_u32 s4, s4, 0x1000
	s_addc_u32 s5, s5, 0
	v_lshl_add_u64 v[176:177], v[114:115], 0, s[4:5]
	global_load_dword v216, v[176:177], off
	global_load_dword v217, v[176:177], off offset:2048
	s_add_u32 s4, s4, 0x1000
	s_addc_u32 s5, s5, 0
	v_lshl_add_u64 v[174:175], v[114:115], 0, s[4:5]
	global_load_dword v218, v[174:175], off
	global_load_dword v219, v[174:175], off offset:2048
	s_add_u32 s4, s4, 0x1000
	s_addc_u32 s5, s5, 0
	v_lshl_add_u64 v[176:177], v[114:115], 0, s[4:5]
	global_load_dword v220, v[176:177], off
	global_load_dword v221, v[176:177], off offset:2048
	s_add_u32 s4, s4, 0x1000
	s_addc_u32 s5, s5, 0
	v_lshl_add_u64 v[174:175], v[114:115], 0, s[4:5]
	global_load_dword v222, v[174:175], off
	global_load_dword v223, v[174:175], off offset:2048
	s_add_u32 s4, s4, 0x1000
	s_addc_u32 s5, s5, 0
	v_lshl_add_u64 v[176:177], v[114:115], 0, s[4:5]
	global_load_dword v224, v[176:177], off
	global_load_dword v225, v[176:177], off offset:2048
	s_add_u32 s4, s4, 0x1000
	s_addc_u32 s5, s5, 0
	v_lshl_add_u64 v[174:175], v[114:115], 0, s[4:5]
	global_load_dword v226, v[174:175], off
	global_load_dword v227, v[174:175], off offset:2048
	s_add_u32 s4, s4, 0x1000
	s_addc_u32 s5, s5, 0
	v_lshl_add_u64 v[176:177], v[114:115], 0, s[4:5]
	global_load_dword v228, v[176:177], off
	global_load_dword v229, v[176:177], off offset:2048
	s_add_u32 s4, s4, 0x1000
	s_addc_u32 s5, s5, 0
	v_lshl_add_u64 v[174:175], v[114:115], 0, s[4:5]
	global_load_dword v230, v[174:175], off
	global_load_dword v231, v[174:175], off offset:2048
	s_add_u32 s4, s4, 0x1000
	s_addc_u32 s5, s5, 0
	v_lshl_add_u64 v[176:177], v[114:115], 0, s[4:5]
	global_load_dword v232, v[176:177], off
	global_load_dword v233, v[176:177], off offset:2048
	s_add_u32 s4, s4, 0x1000
	s_addc_u32 s5, s5, 0
	v_lshl_add_u64 v[174:175], v[114:115], 0, s[4:5]
	global_load_dword v234, v[174:175], off
	global_load_dword v235, v[174:175], off offset:2048
	s_add_u32 s4, s4, 0x1000
	s_addc_u32 s5, s5, 0
	v_lshl_add_u64 v[176:177], v[114:115], 0, s[4:5]
	global_load_dword v236, v[176:177], off
	global_load_dword v237, v[176:177], off offset:2048
	s_add_u32 s4, s4, 0x1000
	s_addc_u32 s5, s5, 0
	v_lshl_add_u64 v[174:175], v[114:115], 0, s[4:5]
	global_load_dword v238, v[174:175], off
	global_load_dword v239, v[174:175], off offset:2048
	s_add_u32 s4, s4, 0x1000
	s_addc_u32 s5, s5, 0
	v_lshl_add_u64 v[176:177], v[114:115], 0, s[4:5]
	global_load_dword v240, v[176:177], off
	global_load_dword v241, v[176:177], off offset:2048
	s_add_u32 s4, s4, 0x1000
	s_addc_u32 s5, s5, 0
	v_lshl_add_u64 v[174:175], v[114:115], 0, s[4:5]
	global_load_dword v242, v[174:175], off
	global_load_dword v243, v[174:175], off offset:2048
	s_add_u32 s4, s4, 0x1000
	s_addc_u32 s5, s5, 0
	v_lshl_add_u64 v[176:177], v[114:115], 0, s[4:5]
	global_load_dword v244, v[176:177], off
	global_load_dword v245, v[176:177], off offset:2048
	s_add_u32 s4, s4, 0x1000
	s_addc_u32 s5, s5, 0
	v_lshl_add_u64 v[174:175], v[114:115], 0, s[4:5]
	global_load_dword v246, v[174:175], off
	global_load_dword v247, v[174:175], off offset:2048
	s_add_u32 s4, s4, 0x1000
	s_addc_u32 s5, s5, 0
	v_lshl_add_u64 v[176:177], v[114:115], 0, s[4:5]
	global_load_dword v248, v[176:177], off
	global_load_dword v249, v[176:177], off offset:2048
	s_add_u32 s4, s4, 0x1000
	s_addc_u32 s5, s5, 0
	v_lshl_add_u64 v[174:175], v[114:115], 0, s[4:5]
	global_load_dword v250, v[174:175], off
	global_load_dword v251, v[174:175], off offset:2048
.Ldw_have:
	s_waitcnt vmcnt(45)
	v_and_b32_e32 v143, 0xffff0000, v206
	s_waitcnt vmcnt(44)
	v_lshlrev_b32_e32 v144, 16, v207
	v_and_b32_e32 v145, 0xffff0000, v207
	s_waitcnt vmcnt(43)
	v_lshlrev_b32_e32 v146, 16, v208
	v_and_b32_e32 v147, 0xffff0000, v208
	s_waitcnt vmcnt(42)
	v_lshlrev_b32_e32 v148, 16, v209
	v_and_b32_e32 v149, 0xffff0000, v209
	s_waitcnt vmcnt(41)
	v_lshlrev_b32_e32 v152, 16, v210
	v_and_b32_e32 v153, 0xffff0000, v210
	s_waitcnt vmcnt(40)
	v_lshlrev_b32_e32 v154, 16, v211
	v_and_b32_e32 v155, 0xffff0000, v211
	s_waitcnt vmcnt(39)
	v_lshlrev_b32_e32 v156, 16, v212
	v_lshlrev_b32_e32 v142, 16, v206
	v_and_b32_e32 v157, 0xffff0000, v212
	s_waitcnt vmcnt(38)
	v_pk_fma_f32 v[142:143], v[54:55], v[142:143], v[112:113]
	v_lshlrev_b32_e32 v158, 16, v213
	v_pk_fma_f32 v[142:143], v[56:57], v[144:145], v[142:143]
	v_pk_fma_f32 v[144:145], v[54:55], v[144:145], v[112:113]
	v_and_b32_e32 v159, 0xffff0000, v213
	s_waitcnt vmcnt(37)
	v_pk_fma_f32 v[142:143], v[58:59], v[146:147], v[142:143]
	v_pk_fma_f32 v[144:145], v[56:57], v[146:147], v[144:145]
	v_pk_fma_f32 v[146:147], v[54:55], v[146:147], v[112:113]
	v_lshlrev_b32_e32 v160, 16, v214
	v_pk_fma_f32 v[142:143], v[50:51], v[148:149], v[142:143]
	v_pk_fma_f32 v[144:145], v[58:59], v[148:149], v[144:145]
	v_pk_fma_f32 v[146:147], v[56:57], v[148:149], v[146:147]
	v_pk_fma_f32 v[148:149], v[54:55], v[148:149], v[112:113]
	v_and_b32_e32 v161, 0xffff0000, v214
	s_waitcnt vmcnt(36)
	v_pk_fma_f32 v[142:143], v[52:53], v[152:153], v[142:143]
	v_pk_fma_f32 v[144:145], v[50:51], v[152:153], v[144:145]
	v_pk_fma_f32 v[146:147], v[58:59], v[152:153], v[146:147]
	v_pk_fma_f32 v[148:149], v[56:57], v[152:153], v[148:149]
	v_pk_fma_f32 v[152:153], v[54:55], v[152:153], v[112:113]
	v_lshlrev_b32_e32 v162, 16, v215
	v_pk_fma_f32 v[142:143], v[60:61], v[154:155], v[142:143]
	v_pk_fma_f32 v[144:145], v[52:53], v[154:155], v[144:145]
	v_pk_fma_f32 v[146:147], v[50:51], v[154:155], v[146:147]
	v_pk_fma_f32 v[148:149], v[58:59], v[154:155], v[148:149]
	v_pk_fma_f32 v[152:153], v[56:57], v[154:155], v[152:153]
	v_pk_fma_f32 v[154:155], v[54:55], v[154:155], v[112:113]
	v_and_b32_e32 v163, 0xffff0000, v215
	s_waitcnt vmcnt(35)
	v_pk_fma_f32 v[142:143], v[62:63], v[156:157], v[142:143]
	v_pk_fma_f32 v[144:145], v[60:61], v[156:157], v[144:145]
	v_pk_fma_f32 v[146:147], v[52:53], v[156:157], v[146:147]
	v_pk_fma_f32 v[148:149], v[50:51], v[156:157], v[148:149]
	v_pk_fma_f32 v[152:153], v[58:59], v[156:157], v[152:153]
	v_pk_fma_f32 v[154:155], v[56:57], v[156:157], v[154:155]
	v_pk_fma_f32 v[156:157], v[54:55], v[156:157], v[112:113]
	v_lshlrev_b32_e32 v164, 16, v216
	v_pk_fma_f32 v[142:143], v[64:65], v[158:159], v[142:143]
	v_pk_fma_f32 v[144:145], v[62:63], v[158:159], v[144:145]
	v_pk_fma_f32 v[146:147], v[60:61], v[158:159], v[146:147]
	v_pk_fma_f32 v[148:149], v[52:53], v[158:159], v[148:149]
	v_pk_fma_f32 v[152:153], v[50:51], v[158:159], v[152:153]
	v_pk_fma_f32 v[154:155], v[58:59], v[158:159], v[154:155]
	v_pk_fma_f32 v[156:157], v[56:57], v[158:159], v[156:157]
	v_pk_fma_f32 v[158:159], v[54:55], v[158:159], v[112:113]
	v_and_b32_e32 v165, 0xffff0000, v216
	s_waitcnt vmcnt(34)
	v_pk_fma_f32 v[142:143], v[66:67], v[160:161], v[142:143]
	v_pk_fma_f32 v[144:145], v[64:65], v[160:161], v[144:145]
	v_pk_fma_f32 v[146:147], v[62:63], v[160:161], v[146:147]
	v_pk_fma_f32 v[148:149], v[60:61], v[160:161], v[148:149]
	v_pk_fma_f32 v[152:153], v[52:53], v[160:161], v[152:153]
	v_pk_fma_f32 v[154:155], v[50:51], v[160:161], v[154:155]
	v_pk_fma_f32 v[156:157], v[58:59], v[160:161], v[156:157]
	v_pk_fma_f32 v[158:159], v[56:57], v[160:161], v[158:159]
	v_pk_fma_f32 v[160:161], v[54:55], v[160:161], v[112:113]
	v_lshlrev_b32_e32 v134, 16, v217
	v_pk_fma_f32 v[142:143], v[68:69], v[162:163], v[142:143]
	v_pk_fma_f32 v[144:145], v[66:67], v[162:163], v[144:145]
	v_pk_fma_f32 v[146:147], v[64:65], v[162:163], v[146:147]
	v_pk_fma_f32 v[148:149], v[62:63], v[162:163], v[148:149]
	v_pk_fma_f32 v[152:153], v[60:61], v[162:163], v[152:153]
	v_pk_fma_f32 v[154:155], v[52:53], v[162:163], v[154:155]
	v_pk_fma_f32 v[156:157], v[50:51], v[162:163], v[156:157]
	v_pk_fma_f32 v[158:159], v[58:59], v[162:163], v[158:159]
	v_pk_fma_f32 v[160:161], v[56:57], v[162:163], v[160:161]
	v_pk_fma_f32 v[162:163], v[54:55], v[162:163], v[112:113]
	v_and_b32_e32 v135, 0xffff0000, v217
	s_waitcnt vmcnt(33)
	v_pk_fma_f32 v[142:143], v[70:71], v[164:165], v[142:143]
	v_pk_fma_f32 v[144:145], v[68:69], v[164:165], v[144:145]
	v_pk_fma_f32 v[146:147], v[66:67], v[164:165], v[146:147]
	v_pk_fma_f32 v[148:149], v[64:65], v[164:165], v[148:149]
	v_pk_fma_f32 v[152:153], v[62:63], v[164:165], v[152:153]
	v_pk_fma_f32 v[154:155], v[60:61], v[164:165], v[154:155]
	v_pk_fma_f32 v[156:157], v[52:53], v[164:165], v[156:157]
	v_pk_fma_f32 v[158:159], v[50:51], v[164:165], v[158:159]
	v_pk_fma_f32 v[160:161], v[58:59], v[164:165], v[160:161]
	v_pk_fma_f32 v[162:163], v[56:57], v[164:165], v[162:163]
	v_pk_fma_f32 v[164:165], v[54:55], v[164:165], v[112:113]
	v_lshlrev_b32_e32 v166, 16, v218
	v_pk_fma_f32 v[142:143], v[72:73], v[134:135], v[142:143]
	v_pk_fma_f32 v[144:145], v[70:71], v[134:135], v[144:145]
	v_pk_fma_f32 v[146:147], v[68:69], v[134:135], v[146:147]
	v_pk_fma_f32 v[148:149], v[66:67], v[134:135], v[148:149]
	v_pk_fma_f32 v[152:153], v[64:65], v[134:135], v[152:153]
	v_pk_fma_f32 v[154:155], v[62:63], v[134:135], v[154:155]
	v_pk_fma_f32 v[156:157], v[60:61], v[134:135], v[156:157]
	v_pk_fma_f32 v[158:159], v[52:53], v[134:135], v[158:159]
	v_pk_fma_f32 v[160:161], v[50:51], v[134:135], v[160:161]
	v_pk_fma_f32 v[162:163], v[58:59], v[134:135], v[162:163]
	v_pk_fma_f32 v[164:165], v[56:57], v[134:135], v[164:165]
	v_pk_fma_f32 v[134:135], v[54:55], v[134:135], v[112:113]
	v_and_b32_e32 v167, 0xffff0000, v218
	s_waitcnt vmcnt(32)
	v_pk_fma_f32 v[136:137], v[74:75], v[166:167], v[142:143]
	v_pk_fma_f32 v[142:143], v[72:73], v[166:167], v[144:145]
	v_pk_fma_f32 v[144:145], v[70:71], v[166:167], v[146:147]
	v_pk_fma_f32 v[146:147], v[68:69], v[166:167], v[148:149]
	v_pk_fma_f32 v[148:149], v[66:67], v[166:167], v[152:153]
	v_pk_fma_f32 v[152:153], v[64:65], v[166:167], v[154:155]
	v_pk_fma_f32 v[154:155], v[62:63], v[166:167], v[156:157]
	v_pk_fma_f32 v[156:157], v[60:61], v[166:167], v[158:159]
	v_pk_fma_f32 v[158:159], v[52:53], v[166:167], v[160:161]
	v_pk_fma_f32 v[160:161], v[50:51], v[166:167], v[162:163]
	v_pk_fma_f32 v[162:163], v[58:59], v[166:167], v[164:165]
	v_pk_fma_f32 v[134:135], v[56:57], v[166:167], v[134:135]
	v_pk_fma_f32 v[164:165], v[54:55], v[166:167], v[112:113]
	v_lshlrev_b32_e32 v166, 16, v219
	v_and_b32_e32 v167, 0xffff0000, v219
	s_waitcnt vmcnt(31)
	v_lshlrev_b32_e32 v168, 16, v220
	v_and_b32_e32 v169, 0xffff0000, v220
	s_waitcnt vmcnt(30)
	v_lshlrev_b32_e32 v170, 16, v221
	v_pk_fma_f32 v[136:137], v[76:77], v[166:167], v[136:137]
	v_pk_fma_f32 v[142:143], v[74:75], v[166:167], v[142:143]
	v_pk_fma_f32 v[144:145], v[72:73], v[166:167], v[144:145]
	v_pk_fma_f32 v[146:147], v[70:71], v[166:167], v[146:147]
	v_pk_fma_f32 v[148:149], v[68:69], v[166:167], v[148:149]
	v_pk_fma_f32 v[152:153], v[66:67], v[166:167], v[152:153]
	v_pk_fma_f32 v[154:155], v[64:65], v[166:167], v[154:155]
	v_pk_fma_f32 v[156:157], v[62:63], v[166:167], v[156:157]
	v_pk_fma_f32 v[158:159], v[60:61], v[166:167], v[158:159]
	v_pk_fma_f32 v[160:161], v[52:53], v[166:167], v[160:161]
	v_pk_fma_f32 v[162:163], v[50:51], v[166:167], v[162:163]
	v_pk_fma_f32 v[134:135], v[58:59], v[166:167], v[134:135]
	v_pk_fma_f32 v[164:165], v[56:57], v[166:167], v[164:165]
	v_pk_fma_f32 v[166:167], v[54:55], v[166:167], v[112:113]
	v_and_b32_e32 v171, 0xffff0000, v221
	s_waitcnt vmcnt(29)
	v_pk_fma_f32 v[136:137], v[78:79], v[168:169], v[136:137]
	v_pk_fma_f32 v[142:143], v[76:77], v[168:169], v[142:143]
	v_pk_fma_f32 v[144:145], v[74:75], v[168:169], v[144:145]
	v_pk_fma_f32 v[146:147], v[72:73], v[168:169], v[146:147]
	v_pk_fma_f32 v[148:149], v[70:71], v[168:169], v[148:149]
	v_pk_fma_f32 v[152:153], v[68:69], v[168:169], v[152:153]
	v_pk_fma_f32 v[154:155], v[66:67], v[168:169], v[154:155]
	v_pk_fma_f32 v[156:157], v[64:65], v[168:169], v[156:157]
	v_pk_fma_f32 v[158:159], v[62:63], v[168:169], v[158:159]
	v_pk_fma_f32 v[160:161], v[60:61], v[168:169], v[160:161]
	v_pk_fma_f32 v[162:163], v[52:53], v[168:169], v[162:163]
	v_pk_fma_f32 v[134:135], v[50:51], v[168:169], v[134:135]
	v_pk_fma_f32 v[164:165], v[58:59], v[168:169], v[164:165]
	v_pk_fma_f32 v[166:167], v[56:57], v[168:169], v[166:167]
	v_pk_fma_f32 v[168:169], v[54:55], v[168:169], v[112:113]
	v_lshlrev_b32_e32 v172, 16, v222
	v_pk_fma_f32 v[136:137], v[80:81], v[170:171], v[136:137]
	v_pk_fma_f32 v[142:143], v[78:79], v[170:171], v[142:143]
	v_pk_fma_f32 v[144:145], v[76:77], v[170:171], v[144:145]
	v_pk_fma_f32 v[146:147], v[74:75], v[170:171], v[146:147]
	v_pk_fma_f32 v[148:149], v[72:73], v[170:171], v[148:149]
	v_pk_fma_f32 v[152:153], v[70:71], v[170:171], v[152:153]
	v_pk_fma_f32 v[154:155], v[68:69], v[170:171], v[154:155]
	v_pk_fma_f32 v[156:157], v[66:67], v[170:171], v[156:157]
	v_pk_fma_f32 v[158:159], v[64:65], v[170:171], v[158:159]
	v_pk_fma_f32 v[160:161], v[62:63], v[170:171], v[160:161]
	v_pk_fma_f32 v[162:163], v[60:61], v[170:171], v[162:163]
	v_pk_fma_f32 v[134:135], v[52:53], v[170:171], v[134:135]
	v_pk_fma_f32 v[164:165], v[50:51], v[170:171], v[164:165]
	v_pk_fma_f32 v[166:167], v[58:59], v[170:171], v[166:167]
	v_pk_fma_f32 v[168:169], v[56:57], v[170:171], v[168:169]
	v_pk_fma_f32 v[170:171], v[54:55], v[170:171], v[112:113]
	v_and_b32_e32 v173, 0xffff0000, v222
	s_waitcnt vmcnt(28)
	v_pk_fma_f32 v[48:49], v[82:83], v[172:173], v[136:137]
	v_pk_fma_f32 v[136:137], v[80:81], v[172:173], v[142:143]
	v_pk_fma_f32 v[142:143], v[78:79], v[172:173], v[144:145]
	v_pk_fma_f32 v[144:145], v[76:77], v[172:173], v[146:147]
	v_pk_fma_f32 v[146:147], v[74:75], v[172:173], v[148:149]
	v_pk_fma_f32 v[148:149], v[72:73], v[172:173], v[152:153]
	v_pk_fma_f32 v[152:153], v[70:71], v[172:173], v[154:155]
	v_pk_fma_f32 v[154:155], v[68:69], v[172:173], v[156:157]
	v_pk_fma_f32 v[156:157], v[66:67], v[172:173], v[158:159]
	v_pk_fma_f32 v[158:159], v[64:65], v[172:173], v[160:161]
	v_pk_fma_f32 v[160:161], v[62:63], v[172:173], v[162:163]
	v_pk_fma_f32 v[162:163], v[52:53], v[172:173], v[164:165]
	v_pk_fma_f32 v[164:165], v[50:51], v[172:173], v[166:167]
	v_pk_fma_f32 v[166:167], v[58:59], v[172:173], v[168:169]
	v_pk_fma_f32 v[168:169], v[56:57], v[172:173], v[170:171]
	v_lshlrev_b32_e32 v170, 16, v223
	v_and_b32_e32 v171, 0xffff0000, v223
	s_waitcnt vmcnt(27)
	v_pk_fma_f32 v[134:135], v[60:61], v[172:173], v[134:135]
	v_pk_fma_f32 v[46:47], v[84:85], v[170:171], v[48:49]
	v_pk_fma_f32 v[48:49], v[82:83], v[170:171], v[136:137]
	v_pk_fma_f32 v[136:137], v[80:81], v[170:171], v[142:143]
	v_pk_fma_f32 v[142:143], v[78:79], v[170:171], v[144:145]
	v_pk_fma_f32 v[144:145], v[76:77], v[170:171], v[146:147]
	v_pk_fma_f32 v[146:147], v[74:75], v[170:171], v[148:149]
	v_pk_fma_f32 v[148:149], v[72:73], v[170:171], v[152:153]
	v_pk_fma_f32 v[152:153], v[70:71], v[170:171], v[154:155]
	v_pk_fma_f32 v[154:155], v[68:69], v[170:171], v[156:157]
	v_pk_fma_f32 v[156:157], v[66:67], v[170:171], v[158:159]
	v_pk_fma_f32 v[158:159], v[64:65], v[170:171], v[160:161]
	v_pk_fma_f32 v[160:161], v[60:61], v[170:171], v[162:163]
	v_pk_fma_f32 v[162:163], v[52:53], v[170:171], v[164:165]
	v_pk_fma_f32 v[164:165], v[50:51], v[170:171], v[166:167]
	v_pk_fma_f32 v[166:167], v[58:59], v[170:171], v[168:169]
	v_lshlrev_b32_e32 v168, 16, v224
	v_pk_fma_f32 v[134:135], v[62:63], v[170:171], v[134:135]
	v_and_b32_e32 v169, 0xffff0000, v224
	s_waitcnt vmcnt(26)
	v_pk_fma_f32 v[46:47], v[86:87], v[168:169], v[46:47]
	v_pk_fma_f32 v[48:49], v[84:85], v[168:169], v[48:49]
	v_pk_fma_f32 v[136:137], v[82:83], v[168:169], v[136:137]
	v_pk_fma_f32 v[142:143], v[80:81], v[168:169], v[142:143]
	v_pk_fma_f32 v[144:145], v[78:79], v[168:169], v[144:145]
	v_pk_fma_f32 v[146:147], v[76:77], v[168:169], v[146:147]
	v_pk_fma_f32 v[148:149], v[74:75], v[168:169], v[148:149]
	v_pk_fma_f32 v[152:153], v[72:73], v[168:169], v[152:153]
	v_pk_fma_f32 v[154:155], v[70:71], v[168:169], v[154:155]
	v_pk_fma_f32 v[156:157], v[68:69], v[168:169], v[156:157]
	v_pk_fma_f32 v[158:159], v[66:67], v[168:169], v[158:159]
	v_pk_fma_f32 v[134:135], v[64:65], v[168:169], v[134:135]
	v_pk_fma_f32 v[160:161], v[62:63], v[168:169], v[160:161]
	v_pk_fma_f32 v[162:163], v[60:61], v[168:169], v[162:163]
	v_pk_fma_f32 v[164:165], v[52:53], v[168:169], v[164:165]
	v_pk_fma_f32 v[166:167], v[50:51], v[168:169], v[166:167]
	v_lshlrev_b32_e32 v168, 16, v225
	v_and_b32_e32 v169, 0xffff0000, v225
	s_waitcnt vmcnt(25)
	v_lshlrev_b32_e32 v38, 16, v226
	v_pk_fma_f32 v[42:43], v[88:89], v[168:169], v[46:47]
	v_pk_fma_f32 v[46:47], v[86:87], v[168:169], v[48:49]
	v_pk_fma_f32 v[48:49], v[84:85], v[168:169], v[136:137]
	v_pk_fma_f32 v[136:137], v[82:83], v[168:169], v[142:143]
	v_pk_fma_f32 v[142:143], v[80:81], v[168:169], v[144:145]
	v_pk_fma_f32 v[144:145], v[78:79], v[168:169], v[146:147]
	v_pk_fma_f32 v[146:147], v[76:77], v[168:169], v[148:149]
	v_pk_fma_f32 v[148:149], v[74:75], v[168:169], v[152:153]
	v_pk_fma_f32 v[152:153], v[72:73], v[168:169], v[154:155]
	v_pk_fma_f32 v[154:155], v[70:71], v[168:169], v[156:157]
	v_pk_fma_f32 v[156:157], v[68:69], v[168:169], v[158:159]
	v_pk_fma_f32 v[134:135], v[66:67], v[168:169], v[134:135]
	v_pk_fma_f32 v[158:159], v[64:65], v[168:169], v[160:161]
	v_pk_fma_f32 v[160:161], v[62:63], v[168:169], v[162:163]
	v_pk_fma_f32 v[162:163], v[60:61], v[168:169], v[164:165]
	v_pk_fma_f32 v[164:165], v[52:53], v[168:169], v[166:167]
	v_and_b32_e32 v39, 0xffff0000, v226
	s_waitcnt vmcnt(24)
	v_pk_fma_f32 v[42:43], v[90:91], v[38:39], v[42:43]
	v_pk_fma_f32 v[46:47], v[88:89], v[38:39], v[46:47]
	v_pk_fma_f32 v[48:49], v[86:87], v[38:39], v[48:49]
	v_pk_fma_f32 v[136:137], v[84:85], v[38:39], v[136:137]
	v_pk_fma_f32 v[142:143], v[82:83], v[38:39], v[142:143]
	v_pk_fma_f32 v[144:145], v[80:81], v[38:39], v[144:145]
	v_pk_fma_f32 v[146:147], v[78:79], v[38:39], v[146:147]
	v_pk_fma_f32 v[148:149], v[76:77], v[38:39], v[148:149]
	v_pk_fma_f32 v[152:153], v[74:75], v[38:39], v[152:153]
	v_pk_fma_f32 v[154:155], v[72:73], v[38:39], v[154:155]
	v_pk_fma_f32 v[156:157], v[70:71], v[38:39], v[156:157]
	v_pk_fma_f32 v[134:135], v[68:69], v[38:39], v[134:135]
	v_pk_fma_f32 v[158:159], v[66:67], v[38:39], v[158:159]
	v_pk_fma_f32 v[160:161], v[64:65], v[38:39], v[160:161]
	v_pk_fma_f32 v[162:163], v[62:63], v[38:39], v[162:163]
	v_pk_fma_f32 v[38:39], v[60:61], v[38:39], v[164:165]
	v_lshlrev_b32_e32 v164, 16, v227
	v_and_b32_e32 v165, 0xffff0000, v227
	s_waitcnt vmcnt(23)
	v_lshlrev_b32_e32 v32, 16, v228
	v_pk_fma_f32 v[42:43], v[92:93], v[164:165], v[42:43]
	v_pk_fma_f32 v[46:47], v[90:91], v[164:165], v[46:47]
	v_pk_fma_f32 v[48:49], v[88:89], v[164:165], v[48:49]
	v_pk_fma_f32 v[136:137], v[86:87], v[164:165], v[136:137]
	v_pk_fma_f32 v[142:143], v[84:85], v[164:165], v[142:143]
	v_pk_fma_f32 v[144:145], v[82:83], v[164:165], v[144:145]
	v_pk_fma_f32 v[146:147], v[80:81], v[164:165], v[146:147]
	v_pk_fma_f32 v[148:149], v[78:79], v[164:165], v[148:149]
	v_pk_fma_f32 v[152:153], v[76:77], v[164:165], v[152:153]
	v_pk_fma_f32 v[154:155], v[74:75], v[164:165], v[154:155]
	v_pk_fma_f32 v[156:157], v[72:73], v[164:165], v[156:157]
	v_pk_fma_f32 v[134:135], v[70:71], v[164:165], v[134:135]
	v_pk_fma_f32 v[158:159], v[68:69], v[164:165], v[158:159]
	v_pk_fma_f32 v[160:161], v[66:67], v[164:165], v[160:161]
	v_pk_fma_f32 v[162:163], v[64:65], v[164:165], v[162:163]
	v_pk_fma_f32 v[38:39], v[62:63], v[164:165], v[38:39]
	v_and_b32_e32 v33, 0xffff0000, v228
	s_waitcnt vmcnt(22)
	v_pk_fma_f32 v[42:43], v[94:95], v[32:33], v[42:43]
	v_pk_fma_f32 v[46:47], v[92:93], v[32:33], v[46:47]
	v_pk_fma_f32 v[48:49], v[90:91], v[32:33], v[48:49]
	v_pk_fma_f32 v[136:137], v[88:89], v[32:33], v[136:137]
	v_pk_fma_f32 v[142:143], v[86:87], v[32:33], v[142:143]
	v_pk_fma_f32 v[144:145], v[84:85], v[32:33], v[144:145]
	v_pk_fma_f32 v[146:147], v[82:83], v[32:33], v[146:147]
	v_pk_fma_f32 v[148:149], v[80:81], v[32:33], v[148:149]
	v_pk_fma_f32 v[152:153], v[78:79], v[32:33], v[152:153]
	v_pk_fma_f32 v[154:155], v[76:77], v[32:33], v[154:155]
	v_pk_fma_f32 v[156:157], v[74:75], v[32:33], v[156:157]
	v_pk_fma_f32 v[134:135], v[72:73], v[32:33], v[134:135]
	v_pk_fma_f32 v[158:159], v[70:71], v[32:33], v[158:159]
	v_pk_fma_f32 v[160:161], v[68:69], v[32:33], v[160:161]
	v_pk_fma_f32 v[162:163], v[66:67], v[32:33], v[162:163]
	v_pk_fma_f32 v[32:33], v[64:65], v[32:33], v[38:39]
	v_lshlrev_b32_e32 v38, 16, v229
	v_and_b32_e32 v39, 0xffff0000, v229
	s_waitcnt vmcnt(21)
	v_pk_fma_f32 v[42:43], v[96:97], v[38:39], v[42:43]
	v_pk_fma_f32 v[46:47], v[94:95], v[38:39], v[46:47]
	v_pk_fma_f32 v[48:49], v[92:93], v[38:39], v[48:49]
	v_pk_fma_f32 v[136:137], v[90:91], v[38:39], v[136:137]
	v_pk_fma_f32 v[142:143], v[88:89], v[38:39], v[142:143]
	v_pk_fma_f32 v[144:145], v[86:87], v[38:39], v[144:145]
	v_pk_fma_f32 v[146:147], v[84:85], v[38:39], v[146:147]
	v_pk_fma_f32 v[148:149], v[82:83], v[38:39], v[148:149]
	v_pk_fma_f32 v[152:153], v[80:81], v[38:39], v[152:153]
	v_pk_fma_f32 v[154:155], v[78:79], v[38:39], v[154:155]
	v_pk_fma_f32 v[156:157], v[76:77], v[38:39], v[156:157]
	v_pk_fma_f32 v[134:135], v[74:75], v[38:39], v[134:135]
	v_pk_fma_f32 v[158:159], v[72:73], v[38:39], v[158:159]
	v_pk_fma_f32 v[160:161], v[70:71], v[38:39], v[160:161]
	v_pk_fma_f32 v[162:163], v[68:69], v[38:39], v[162:163]
	v_pk_fma_f32 v[32:33], v[66:67], v[38:39], v[32:33]
	v_lshlrev_b32_e32 v38, 16, v230
	v_and_b32_e32 v39, 0xffff0000, v230
	s_waitcnt vmcnt(20)
	v_lshlrev_b32_e32 v36, 16, v231
	v_pk_fma_f32 v[40:41], v[98:99], v[38:39], v[42:43]
	v_pk_fma_f32 v[42:43], v[96:97], v[38:39], v[46:47]
	v_pk_fma_f32 v[46:47], v[94:95], v[38:39], v[48:49]
	v_pk_fma_f32 v[48:49], v[92:93], v[38:39], v[136:137]
	v_pk_fma_f32 v[136:137], v[90:91], v[38:39], v[142:143]
	v_pk_fma_f32 v[142:143], v[88:89], v[38:39], v[144:145]
	v_pk_fma_f32 v[144:145], v[86:87], v[38:39], v[146:147]
	v_pk_fma_f32 v[146:147], v[84:85], v[38:39], v[148:149]
	v_pk_fma_f32 v[148:149], v[82:83], v[38:39], v[152:153]
	v_pk_fma_f32 v[152:153], v[80:81], v[38:39], v[154:155]
	v_pk_fma_f32 v[154:155], v[78:79], v[38:39], v[156:157]
	v_pk_fma_f32 v[134:135], v[76:77], v[38:39], v[134:135]
	v_pk_fma_f32 v[156:157], v[74:75], v[38:39], v[158:159]
	v_pk_fma_f32 v[158:159], v[72:73], v[38:39], v[160:161]
	v_pk_fma_f32 v[160:161], v[70:71], v[38:39], v[162:163]
	v_pk_fma_f32 v[32:33], v[68:69], v[38:39], v[32:33]
	v_and_b32_e32 v37, 0xffff0000, v231
	s_waitcnt vmcnt(19)
	v_pk_fma_f32 v[38:39], v[100:101], v[36:37], v[40:41]
	v_pk_fma_f32 v[40:41], v[98:99], v[36:37], v[42:43]
	v_pk_fma_f32 v[42:43], v[96:97], v[36:37], v[46:47]
	v_pk_fma_f32 v[46:47], v[94:95], v[36:37], v[48:49]
	v_pk_fma_f32 v[48:49], v[92:93], v[36:37], v[136:137]
	v_pk_fma_f32 v[136:137], v[90:91], v[36:37], v[142:143]
	v_pk_fma_f32 v[142:143], v[88:89], v[36:37], v[144:145]
	v_pk_fma_f32 v[144:145], v[86:87], v[36:37], v[146:147]
	v_pk_fma_f32 v[146:147], v[84:85], v[36:37], v[148:149]
	v_pk_fma_f32 v[148:149], v[82:83], v[36:37], v[152:153]
	v_pk_fma_f32 v[152:153], v[80:81], v[36:37], v[154:155]
	v_pk_fma_f32 v[134:135], v[78:79], v[36:37], v[134:135]
	v_pk_fma_f32 v[154:155], v[76:77], v[36:37], v[156:157]
	v_pk_fma_f32 v[156:157], v[74:75], v[36:37], v[158:159]
	v_pk_fma_f32 v[158:159], v[72:73], v[36:37], v[160:161]
	v_pk_fma_f32 v[32:33], v[70:71], v[36:37], v[32:33]
	v_lshlrev_b32_e32 v36, 16, v232
	v_and_b32_e32 v37, 0xffff0000, v232
	s_waitcnt vmcnt(18)
	v_pk_fma_f32 v[38:39], v[102:103], v[36:37], v[38:39]
	v_pk_fma_f32 v[40:41], v[100:101], v[36:37], v[40:41]
	v_pk_fma_f32 v[42:43], v[98:99], v[36:37], v[42:43]
	v_pk_fma_f32 v[46:47], v[96:97], v[36:37], v[46:47]
	v_pk_fma_f32 v[48:49], v[94:95], v[36:37], v[48:49]
	v_pk_fma_f32 v[136:137], v[92:93], v[36:37], v[136:137]
	v_pk_fma_f32 v[142:143], v[90:91], v[36:37], v[142:143]
	v_pk_fma_f32 v[144:145], v[88:89], v[36:37], v[144:145]
	v_pk_fma_f32 v[146:147], v[86:87], v[36:37], v[146:147]
	v_pk_fma_f32 v[148:149], v[84:85], v[36:37], v[148:149]
	v_pk_fma_f32 v[152:153], v[82:83], v[36:37], v[152:153]
	v_pk_fma_f32 v[134:135], v[80:81], v[36:37], v[134:135]
	v_pk_fma_f32 v[154:155], v[78:79], v[36:37], v[154:155]
	v_pk_fma_f32 v[156:157], v[76:77], v[36:37], v[156:157]
	v_pk_fma_f32 v[158:159], v[74:75], v[36:37], v[158:159]
	v_pk_fma_f32 v[32:33], v[72:73], v[36:37], v[32:33]
	v_lshlrev_b32_e32 v36, 16, v233
	v_and_b32_e32 v37, 0xffff0000, v233
	s_waitcnt vmcnt(17)
	v_pk_fma_f32 v[38:39], v[104:105], v[36:37], v[38:39]
	v_pk_fma_f32 v[40:41], v[102:103], v[36:37], v[40:41]
	v_pk_fma_f32 v[42:43], v[100:101], v[36:37], v[42:43]
	v_pk_fma_f32 v[46:47], v[98:99], v[36:37], v[46:47]
	v_pk_fma_f32 v[48:49], v[96:97], v[36:37], v[48:49]
	v_pk_fma_f32 v[136:137], v[94:95], v[36:37], v[136:137]
	v_pk_fma_f32 v[142:143], v[92:93], v[36:37], v[142:143]
	v_pk_fma_f32 v[144:145], v[90:91], v[36:37], v[144:145]
	v_pk_fma_f32 v[146:147], v[88:89], v[36:37], v[146:147]
	v_pk_fma_f32 v[148:149], v[86:87], v[36:37], v[148:149]
	v_pk_fma_f32 v[152:153], v[84:85], v[36:37], v[152:153]
	v_pk_fma_f32 v[134:135], v[82:83], v[36:37], v[134:135]
	v_pk_fma_f32 v[154:155], v[80:81], v[36:37], v[154:155]
	v_pk_fma_f32 v[156:157], v[78:79], v[36:37], v[156:157]
	v_pk_fma_f32 v[158:159], v[76:77], v[36:37], v[158:159]
	v_pk_fma_f32 v[32:33], v[74:75], v[36:37], v[32:33]
	v_lshlrev_b32_e32 v36, 16, v234
	v_and_b32_e32 v37, 0xffff0000, v234
	s_waitcnt vmcnt(16)
	v_pk_fma_f32 v[38:39], v[106:107], v[36:37], v[38:39]
	v_pk_fma_f32 v[40:41], v[104:105], v[36:37], v[40:41]
	v_pk_fma_f32 v[42:43], v[102:103], v[36:37], v[42:43]
	v_pk_fma_f32 v[46:47], v[100:101], v[36:37], v[46:47]
	v_pk_fma_f32 v[48:49], v[98:99], v[36:37], v[48:49]
	v_pk_fma_f32 v[136:137], v[96:97], v[36:37], v[136:137]
	v_pk_fma_f32 v[142:143], v[94:95], v[36:37], v[142:143]
	v_pk_fma_f32 v[144:145], v[92:93], v[36:37], v[144:145]
	v_pk_fma_f32 v[146:147], v[90:91], v[36:37], v[146:147]
	v_pk_fma_f32 v[148:149], v[88:89], v[36:37], v[148:149]
	v_pk_fma_f32 v[152:153], v[86:87], v[36:37], v[152:153]
	v_pk_fma_f32 v[134:135], v[84:85], v[36:37], v[134:135]
	v_pk_fma_f32 v[154:155], v[82:83], v[36:37], v[154:155]
	v_pk_fma_f32 v[156:157], v[80:81], v[36:37], v[156:157]
	v_pk_fma_f32 v[158:159], v[78:79], v[36:37], v[158:159]
	v_pk_fma_f32 v[32:33], v[76:77], v[36:37], v[32:33]
	v_lshlrev_b32_e32 v36, 16, v235
	v_and_b32_e32 v37, 0xffff0000, v235
	s_waitcnt vmcnt(15)
	v_lshlrev_b32_e32 v18, 16, v236
	v_pk_fma_f32 v[20:21], v[108:109], v[36:37], v[38:39]
	v_pk_fma_f32 v[38:39], v[106:107], v[36:37], v[40:41]
	v_pk_fma_f32 v[40:41], v[104:105], v[36:37], v[42:43]
	v_pk_fma_f32 v[42:43], v[102:103], v[36:37], v[46:47]
	v_pk_fma_f32 v[46:47], v[100:101], v[36:37], v[48:49]
	v_pk_fma_f32 v[48:49], v[98:99], v[36:37], v[136:137]
	v_pk_fma_f32 v[136:137], v[96:97], v[36:37], v[142:143]
	v_pk_fma_f32 v[142:143], v[94:95], v[36:37], v[144:145]
	v_pk_fma_f32 v[144:145], v[92:93], v[36:37], v[146:147]
	v_pk_fma_f32 v[146:147], v[90:91], v[36:37], v[148:149]
	v_pk_fma_f32 v[148:149], v[88:89], v[36:37], v[152:153]
	v_pk_fma_f32 v[134:135], v[86:87], v[36:37], v[134:135]
	v_pk_fma_f32 v[152:153], v[84:85], v[36:37], v[154:155]
	v_pk_fma_f32 v[154:155], v[82:83], v[36:37], v[156:157]
	v_pk_fma_f32 v[156:157], v[80:81], v[36:37], v[158:159]
	v_pk_fma_f32 v[32:33], v[78:79], v[36:37], v[32:33]
	v_and_b32_e32 v19, 0xffff0000, v236
	s_waitcnt vmcnt(14)
	v_pk_fma_f32 v[20:21], v[110:111], v[18:19], v[20:21]
	v_pk_fma_f32 v[36:37], v[108:109], v[18:19], v[38:39]
	v_pk_fma_f32 v[38:39], v[106:107], v[18:19], v[40:41]
	v_pk_fma_f32 v[40:41], v[104:105], v[18:19], v[42:43]
	v_pk_fma_f32 v[42:43], v[102:103], v[18:19], v[46:47]
	v_pk_fma_f32 v[46:47], v[100:101], v[18:19], v[48:49]
	v_pk_fma_f32 v[48:49], v[98:99], v[18:19], v[136:137]
	v_pk_fma_f32 v[136:137], v[96:97], v[18:19], v[142:143]
	v_pk_fma_f32 v[142:143], v[94:95], v[18:19], v[144:145]
	v_pk_fma_f32 v[144:145], v[92:93], v[18:19], v[146:147]
	v_pk_fma_f32 v[146:147], v[90:91], v[18:19], v[148:149]
	v_pk_fma_f32 v[134:135], v[88:89], v[18:19], v[134:135]
	v_pk_fma_f32 v[148:149], v[86:87], v[18:19], v[152:153]
	v_pk_fma_f32 v[152:153], v[84:85], v[18:19], v[154:155]
	v_pk_fma_f32 v[154:155], v[82:83], v[18:19], v[156:157]
	v_pk_fma_f32 v[18:19], v[80:81], v[18:19], v[32:33]
	v_lshlrev_b32_e32 v32, 16, v237
	v_and_b32_e32 v33, 0xffff0000, v237
	s_waitcnt vmcnt(13)
	v_lshlrev_b32_e32 v30, 16, v238
	v_pk_fma_f32 v[38:39], v[108:109], v[32:33], v[38:39]
	v_pk_fma_f32 v[40:41], v[106:107], v[32:33], v[40:41]
	v_pk_fma_f32 v[42:43], v[104:105], v[32:33], v[42:43]
	v_pk_fma_f32 v[46:47], v[102:103], v[32:33], v[46:47]
	v_pk_fma_f32 v[48:49], v[100:101], v[32:33], v[48:49]
	v_pk_fma_f32 v[136:137], v[98:99], v[32:33], v[136:137]
	v_pk_fma_f32 v[142:143], v[96:97], v[32:33], v[142:143]
	v_pk_fma_f32 v[144:145], v[94:95], v[32:33], v[144:145]
	v_pk_fma_f32 v[146:147], v[92:93], v[32:33], v[146:147]
	v_pk_fma_f32 v[134:135], v[90:91], v[32:33], v[134:135]
	v_pk_fma_f32 v[148:149], v[88:89], v[32:33], v[148:149]
	v_pk_fma_f32 v[152:153], v[86:87], v[32:33], v[152:153]
	v_pk_fma_f32 v[154:155], v[84:85], v[32:33], v[154:155]
	v_pk_fma_f32 v[18:19], v[82:83], v[32:33], v[18:19]
	v_and_b32_e32 v31, 0xffff0000, v238
	s_waitcnt vmcnt(12)
	v_pk_fma_f32 v[36:37], v[110:111], v[32:33], v[36:37]
	v_pk_fma_f32 v[32:33], v[110:111], v[30:31], v[38:39]
	v_pk_fma_f32 v[38:39], v[108:109], v[30:31], v[40:41]
	v_pk_fma_f32 v[40:41], v[106:107], v[30:31], v[42:43]
	v_pk_fma_f32 v[42:43], v[104:105], v[30:31], v[46:47]
	v_pk_fma_f32 v[46:47], v[102:103], v[30:31], v[48:49]
	v_pk_fma_f32 v[48:49], v[100:101], v[30:31], v[136:137]
	v_pk_fma_f32 v[136:137], v[98:99], v[30:31], v[142:143]
	v_pk_fma_f32 v[142:143], v[96:97], v[30:31], v[144:145]
	v_pk_fma_f32 v[144:145], v[94:95], v[30:31], v[146:147]
	v_pk_fma_f32 v[134:135], v[92:93], v[30:31], v[134:135]
	v_pk_fma_f32 v[146:147], v[90:91], v[30:31], v[148:149]
	v_pk_fma_f32 v[148:149], v[88:89], v[30:31], v[152:153]
	v_pk_fma_f32 v[152:153], v[86:87], v[30:31], v[154:155]
	v_pk_fma_f32 v[18:19], v[84:85], v[30:31], v[18:19]
	v_lshlrev_b32_e32 v30, 16, v239
	v_and_b32_e32 v31, 0xffff0000, v239
	s_waitcnt vmcnt(11)
	v_lshlrev_b32_e32 v22, 16, v240
	v_pk_fma_f32 v[40:41], v[108:109], v[30:31], v[40:41]
	v_pk_fma_f32 v[42:43], v[106:107], v[30:31], v[42:43]
	v_pk_fma_f32 v[46:47], v[104:105], v[30:31], v[46:47]
	v_pk_fma_f32 v[48:49], v[102:103], v[30:31], v[48:49]
	v_pk_fma_f32 v[136:137], v[100:101], v[30:31], v[136:137]
	v_pk_fma_f32 v[142:143], v[98:99], v[30:31], v[142:143]
	v_pk_fma_f32 v[144:145], v[96:97], v[30:31], v[144:145]
	v_pk_fma_f32 v[134:135], v[94:95], v[30:31], v[134:135]
	v_pk_fma_f32 v[146:147], v[92:93], v[30:31], v[146:147]
	v_pk_fma_f32 v[148:149], v[90:91], v[30:31], v[148:149]
	v_pk_fma_f32 v[152:153], v[88:89], v[30:31], v[152:153]
	v_pk_fma_f32 v[18:19], v[86:87], v[30:31], v[18:19]
	v_and_b32_e32 v23, 0xffff0000, v240
	s_waitcnt vmcnt(10)
	v_pk_fma_f32 v[38:39], v[110:111], v[30:31], v[38:39]
	v_pk_fma_f32 v[30:31], v[110:111], v[22:23], v[40:41]
	v_pk_fma_f32 v[40:41], v[108:109], v[22:23], v[42:43]
	v_pk_fma_f32 v[42:43], v[106:107], v[22:23], v[46:47]
	v_pk_fma_f32 v[46:47], v[104:105], v[22:23], v[48:49]
	v_pk_fma_f32 v[48:49], v[102:103], v[22:23], v[136:137]
	v_pk_fma_f32 v[136:137], v[100:101], v[22:23], v[142:143]
	v_pk_fma_f32 v[142:143], v[98:99], v[22:23], v[144:145]
	v_pk_fma_f32 v[134:135], v[96:97], v[22:23], v[134:135]
	v_pk_fma_f32 v[144:145], v[94:95], v[22:23], v[146:147]
	v_pk_fma_f32 v[146:147], v[92:93], v[22:23], v[148:149]
	v_pk_fma_f32 v[148:149], v[90:91], v[22:23], v[152:153]
	v_pk_fma_f32 v[18:19], v[88:89], v[22:23], v[18:19]
	v_lshlrev_b32_e32 v22, 16, v241
	v_and_b32_e32 v23, 0xffff0000, v241
	s_waitcnt vmcnt(9)
	v_pk_fma_f32 v[24:25], v[110:111], v[22:23], v[40:41]
	v_pk_fma_f32 v[40:41], v[108:109], v[22:23], v[42:43]
	v_pk_fma_f32 v[42:43], v[106:107], v[22:23], v[46:47]
	v_pk_fma_f32 v[46:47], v[104:105], v[22:23], v[48:49]
	v_pk_fma_f32 v[48:49], v[102:103], v[22:23], v[136:137]
	v_pk_fma_f32 v[136:137], v[100:101], v[22:23], v[142:143]
	v_pk_fma_f32 v[134:135], v[98:99], v[22:23], v[134:135]
	v_pk_fma_f32 v[142:143], v[96:97], v[22:23], v[144:145]
	v_pk_fma_f32 v[144:145], v[94:95], v[22:23], v[146:147]
	v_pk_fma_f32 v[146:147], v[92:93], v[22:23], v[148:149]
	v_pk_fma_f32 v[18:19], v[90:91], v[22:23], v[18:19]
	v_lshlrev_b32_e32 v22, 16, v242
	v_and_b32_e32 v23, 0xffff0000, v242
	s_waitcnt vmcnt(8)
	v_pk_fma_f32 v[26:27], v[110:111], v[22:23], v[40:41]
	v_pk_fma_f32 v[40:41], v[108:109], v[22:23], v[42:43]
	v_pk_fma_f32 v[42:43], v[106:107], v[22:23], v[46:47]
	v_pk_fma_f32 v[46:47], v[104:105], v[22:23], v[48:49]
	v_pk_fma_f32 v[48:49], v[102:103], v[22:23], v[136:137]
	v_pk_fma_f32 v[134:135], v[100:101], v[22:23], v[134:135]
	v_pk_fma_f32 v[136:137], v[98:99], v[22:23], v[142:143]
	v_pk_fma_f32 v[142:143], v[96:97], v[22:23], v[144:145]
	v_pk_fma_f32 v[144:145], v[94:95], v[22:23], v[146:147]
	v_pk_fma_f32 v[18:19], v[92:93], v[22:23], v[18:19]
	v_lshlrev_b32_e32 v22, 16, v243
	v_and_b32_e32 v23, 0xffff0000, v243
	s_waitcnt vmcnt(7)
	v_pk_fma_f32 v[28:29], v[110:111], v[22:23], v[40:41]
	v_pk_fma_f32 v[40:41], v[108:109], v[22:23], v[42:43]
	v_pk_fma_f32 v[42:43], v[106:107], v[22:23], v[46:47]
	v_pk_fma_f32 v[46:47], v[104:105], v[22:23], v[48:49]
	v_pk_fma_f32 v[48:49], v[102:103], v[22:23], v[134:135]
	v_pk_fma_f32 v[134:135], v[100:101], v[22:23], v[136:137]
	v_pk_fma_f32 v[136:137], v[98:99], v[22:23], v[142:143]
	v_pk_fma_f32 v[142:143], v[96:97], v[22:23], v[144:145]
	v_pk_fma_f32 v[18:19], v[94:95], v[22:23], v[18:19]
	v_lshlrev_b32_e32 v22, 16, v244
	v_and_b32_e32 v23, 0xffff0000, v244
	s_waitcnt vmcnt(6)
	v_pk_fma_f32 v[34:35], v[110:111], v[22:23], v[40:41]
	v_pk_fma_f32 v[40:41], v[108:109], v[22:23], v[42:43]
	v_pk_fma_f32 v[42:43], v[106:107], v[22:23], v[46:47]
	v_pk_fma_f32 v[46:47], v[104:105], v[22:23], v[48:49]
	v_pk_fma_f32 v[48:49], v[102:103], v[22:23], v[134:135]
	v_pk_fma_f32 v[134:135], v[100:101], v[22:23], v[136:137]
	v_pk_fma_f32 v[136:137], v[98:99], v[22:23], v[142:143]
	v_pk_fma_f32 v[18:19], v[96:97], v[22:23], v[18:19]
	v_lshlrev_b32_e32 v22, 16, v245
	v_and_b32_e32 v23, 0xffff0000, v245
	s_waitcnt vmcnt(5)
	v_pk_fma_f32 v[40:41], v[110:111], v[22:23], v[40:41]
	v_pk_fma_f32 v[42:43], v[108:109], v[22:23], v[42:43]
	v_pk_fma_f32 v[44:45], v[106:107], v[22:23], v[46:47]
	v_pk_fma_f32 v[46:47], v[104:105], v[22:23], v[48:49]
	v_pk_fma_f32 v[48:49], v[102:103], v[22:23], v[134:135]
	v_pk_fma_f32 v[134:135], v[100:101], v[22:23], v[136:137]
	v_pk_fma_f32 v[18:19], v[98:99], v[22:23], v[18:19]
	v_lshlrev_b32_e32 v22, 16, v246
	v_and_b32_e32 v23, 0xffff0000, v246
	s_waitcnt vmcnt(4)
	v_pk_fma_f32 v[42:43], v[110:111], v[22:23], v[42:43]
	v_pk_fma_f32 v[44:45], v[108:109], v[22:23], v[44:45]
	v_pk_fma_f32 v[46:47], v[106:107], v[22:23], v[46:47]
	v_pk_fma_f32 v[48:49], v[104:105], v[22:23], v[48:49]
	v_pk_fma_f32 v[118:119], v[102:103], v[22:23], v[134:135]
	v_pk_fma_f32 v[18:19], v[100:101], v[22:23], v[18:19]
	v_lshlrev_b32_e32 v22, 16, v247
	v_and_b32_e32 v23, 0xffff0000, v247
	s_waitcnt vmcnt(3)
	v_pk_fma_f32 v[44:45], v[110:111], v[22:23], v[44:45]
	v_pk_fma_f32 v[46:47], v[108:109], v[22:23], v[46:47]
	v_pk_fma_f32 v[48:49], v[106:107], v[22:23], v[48:49]
	v_pk_fma_f32 v[118:119], v[104:105], v[22:23], v[118:119]
	v_pk_fma_f32 v[18:19], v[102:103], v[22:23], v[18:19]
	v_lshlrev_b32_e32 v22, 16, v248
	v_and_b32_e32 v23, 0xffff0000, v248
	s_waitcnt vmcnt(2)
	v_pk_fma_f32 v[46:47], v[110:111], v[22:23], v[46:47]
	v_pk_fma_f32 v[48:49], v[108:109], v[22:23], v[48:49]
	v_pk_fma_f32 v[118:119], v[106:107], v[22:23], v[118:119]
	v_pk_fma_f32 v[18:19], v[104:105], v[22:23], v[18:19]
	v_lshlrev_b32_e32 v22, 16, v249
	v_and_b32_e32 v23, 0xffff0000, v249
	s_waitcnt vmcnt(1)
	v_pk_fma_f32 v[48:49], v[110:111], v[22:23], v[48:49]
	v_pk_fma_f32 v[118:119], v[108:109], v[22:23], v[118:119]
	v_pk_fma_f32 v[18:19], v[106:107], v[22:23], v[18:19]
	v_lshlrev_b32_e32 v22, 16, v250
	v_and_b32_e32 v23, 0xffff0000, v250
	s_waitcnt vmcnt(0)
	v_pk_fma_f32 v[118:119], v[110:111], v[22:23], v[118:119]
	v_pk_fma_f32 v[18:19], v[108:109], v[22:23], v[18:19]
	v_lshlrev_b32_e32 v22, 16, v251
	v_and_b32_e32 v23, 0xffff0000, v251
	v_pk_fma_f32 v[18:19], v[110:111], v[22:23], v[18:19]
	s_add_i32 s3, s94, s70
	v_readlane_b32 s0, v254, 23
	s_sub_i32 s4, s3, 1
	s_cmpk_lt_u32 s4, 0x3fe
	s_cselect_b32 s5, 1, 0
	s_sub_i32 s4, s3, 0x401
	s_cmp_lt_u32 s4, 14
	s_cselect_b32 s4, 1, 0
	s_or_b32 s5, s5, s4
	s_cmp_lt_i32 s3, s0
	s_cselect_b32 s5, s5, 0
	v_writelane_b32 v255, s5, 22
	s_cmp_eq_u32 s5, 0
	s_cbranch_scc1 .Ldw_tail
	s_add_i32 s4, s2, s84
	s_add_i32 s4, s4, -15
	s_ashr_i32 s5, s4, 31
	s_lshl_b64 s[4:5], s[4:5], 11
	v_lshl_add_u64 v[174:175], v[114:115], 0, s[4:5]
	global_load_dword v206, v[174:175], off
	global_load_dword v207, v[174:175], off offset:2048
	s_add_u32 s4, s4, 0x1000
	s_addc_u32 s5, s5, 0
	v_lshl_add_u64 v[176:177], v[114:115], 0, s[4:5]
	global_load_dword v208, v[176:177], off
	global_load_dword v209, v[176:177], off offset:2048
	s_add_u32 s4, s4, 0x1000
	s_addc_u32 s5, s5, 0
	v_lshl_add_u64 v[174:175], v[114:115], 0, s[4:5]
	global_load_dword v210, v[174:175], off
	global_load_dword v211, v[174:175], off offset:2048
	s_add_u32 s4, s4, 0x1000
	s_addc_u32 s5, s5, 0
	v_lshl_add_u64 v[176:177], v[114:115], 0, s[4:5]
	global_load_dword v212, v[176:177], off
	global_load_dword v213, v[176:177], off offset:2048
	s_add_u32 s4, s4, 0x1000
	s_addc_u32 s5, s5, 0
	v_lshl_add_u64 v[174:175], v[114:115], 0, s[4:5]
	global_load_dword v214, v[174:175], off
	global_load_dword v215, v[174:175], off offset:2048
	s_add_u32 s4, s4, 0x1000
	s_addc_u32 s5, s5, 0
	v_lshl_add_u64 v[176:177], v[114:115], 0, s[4:5]
	global_load_dword v216, v[176:177], off
	global_load_dword v217, v[176:177], off offset:2048
	s_add_u32 s4, s4, 0x1000
	s_addc_u32 s5, s5, 0
	v_lshl_add_u64 v[174:175], v[114:115], 0, s[4:5]
	global_load_dword v218, v[174:175], off
	global_load_dword v219, v[174:175], off offset:2048
	s_add_u32 s4, s4, 0x1000
	s_addc_u32 s5, s5, 0
	v_lshl_add_u64 v[176:177], v[114:115], 0, s[4:5]
	global_load_dword v220, v[176:177], off
	global_load_dword v221, v[176:177], off offset:2048
	s_add_u32 s4, s4, 0x1000
	s_addc_u32 s5, s5, 0
	v_lshl_add_u64 v[174:175], v[114:115], 0, s[4:5]
	global_load_dword v222, v[174:175], off
	global_load_dword v223, v[174:175], off offset:2048
	s_add_u32 s4, s4, 0x1000
	s_addc_u32 s5, s5, 0
	v_lshl_add_u64 v[176:177], v[114:115], 0, s[4:5]
	global_load_dword v224, v[176:177], off
	global_load_dword v225, v[176:177], off offset:2048
	s_add_u32 s4, s4, 0x1000
	s_addc_u32 s5, s5, 0
	v_lshl_add_u64 v[174:175], v[114:115], 0, s[4:5]
	global_load_dword v226, v[174:175], off
	global_load_dword v227, v[174:175], off offset:2048
	s_add_u32 s4, s4, 0x1000
	s_addc_u32 s5, s5, 0
	v_lshl_add_u64 v[176:177], v[114:115], 0, s[4:5]
	global_load_dword v228, v[176:177], off
	global_load_dword v229, v[176:177], off offset:2048
	s_add_u32 s4, s4, 0x1000
	s_addc_u32 s5, s5, 0
	v_lshl_add_u64 v[174:175], v[114:115], 0, s[4:5]
	global_load_dword v230, v[174:175], off
	global_load_dword v231, v[174:175], off offset:2048
	s_add_u32 s4, s4, 0x1000
	s_addc_u32 s5, s5, 0
	v_lshl_add_u64 v[176:177], v[114:115], 0, s[4:5]
	global_load_dword v232, v[176:177], off
	global_load_dword v233, v[176:177], off offset:2048
	s_add_u32 s4, s4, 0x1000
	s_addc_u32 s5, s5, 0
	v_lshl_add_u64 v[174:175], v[114:115], 0, s[4:5]
	global_load_dword v234, v[174:175], off
	global_load_dword v235, v[174:175], off offset:2048
	s_add_u32 s4, s4, 0x1000
	s_addc_u32 s5, s5, 0
	v_lshl_add_u64 v[176:177], v[114:115], 0, s[4:5]
	global_load_dword v236, v[176:177], off
	global_load_dword v237, v[176:177], off offset:2048
	s_add_u32 s4, s4, 0x1000
	s_addc_u32 s5, s5, 0
	v_lshl_add_u64 v[174:175], v[114:115], 0, s[4:5]
	global_load_dword v238, v[174:175], off
	global_load_dword v239, v[174:175], off offset:2048
	s_add_u32 s4, s4, 0x1000
	s_addc_u32 s5, s5, 0
	v_lshl_add_u64 v[176:177], v[114:115], 0, s[4:5]
	global_load_dword v240, v[176:177], off
	global_load_dword v241, v[176:177], off offset:2048
	s_add_u32 s4, s4, 0x1000
	s_addc_u32 s5, s5, 0
	v_lshl_add_u64 v[174:175], v[114:115], 0, s[4:5]
	global_load_dword v242, v[174:175], off
	global_load_dword v243, v[174:175], off offset:2048
	s_add_u32 s4, s4, 0x1000
	s_addc_u32 s5, s5, 0
	v_lshl_add_u64 v[176:177], v[114:115], 0, s[4:5]
	global_load_dword v244, v[176:177], off
	global_load_dword v245, v[176:177], off offset:2048
	s_add_u32 s4, s4, 0x1000
	s_addc_u32 s5, s5, 0
	v_lshl_add_u64 v[174:175], v[114:115], 0, s[4:5]
	global_load_dword v246, v[174:175], off
	global_load_dword v247, v[174:175], off offset:2048
	s_add_u32 s4, s4, 0x1000
	s_addc_u32 s5, s5, 0
	v_lshl_add_u64 v[176:177], v[114:115], 0, s[4:5]
	global_load_dword v248, v[176:177], off
	global_load_dword v249, v[176:177], off offset:2048
	s_add_u32 s4, s4, 0x1000
	s_addc_u32 s5, s5, 0
	v_lshl_add_u64 v[174:175], v[114:115], 0, s[4:5]
	global_load_dword v250, v[174:175], off
	global_load_dword v251, v[174:175], off offset:2048
	s_branch .Ldw_tail

.LBB0_498:
	s_andn2_b64 vcc, exec, s[0:1]
	s_cbranch_vccnz .LBB0_503
	v_mov_b32_e32 v0, v178
	s_waitcnt vmcnt(3)
	v_mov_b32_e32 v2, s48
	s_waitcnt vmcnt(2)
	ds_read_b64 v[6:7], v2
	v_readlane_b32 s0, v253, 12
	v_readlane_b32 s2, v253, 13
	v_readlane_b32 s8, v254, 27
	v_mov_b32_e32 v2, s0
	s_waitcnt lgkmcnt(0)
	v_readfirstlane_b32 s0, v6
	v_mov_b32_e32 v6, s2
	ds_read_b128 v[2:5], v2
	v_readfirstlane_b32 s1, v7
	ds_read_b64 v[6:7], v6
	v_readlane_b32 s9, v254, 28
	s_andn2_b64 vcc, exec, s[8:9]
	s_waitcnt lgkmcnt(1)
	v_readfirstlane_b32 s6, v3
	v_readfirstlane_b32 s7, v2
	v_readfirstlane_b32 s3, v5
	v_readfirstlane_b32 s4, v4
	s_waitcnt lgkmcnt(0)
	v_readfirstlane_b32 s2, v7
	v_readfirstlane_b32 s5, v6
	s_cbranch_vccnz .LBB0_503
	v_readlane_b32 s8, v254, 48
	v_lshlrev_b32_e32 v18, 1, v0
	s_add_u32 s8, s7, s8
	v_ashrrev_i32_e32 v19, 31, v18
	s_addc_u32 s9, s6, 0
	v_lshlrev_b64 v[2:3], 2, v[18:19]
	v_lshl_add_u64 v[4:5], s[8:9], 0, v[2:3]
	v_add_co_u32_e32 v6, vcc, 0x1000, v4
	s_movk_i32 s6, 0x6000
	s_nop 0
	v_addc_co_u32_e32 v7, vcc, 0, v5, vcc
	v_add_co_u32_e32 v8, vcc, 0x2000, v4
	v_readlane_b32 s8, v254, 55
	s_nop 0
	v_addc_co_u32_e32 v9, vcc, 0, v5, vcc
	s_waitcnt vmcnt(1)
	v_add_co_u32_e32 v10, vcc, s86, v4
	v_readlane_b32 s9, v254, 56
	s_nop 0
	v_addc_co_u32_e32 v11, vcc, 0, v5, vcc
	global_load_dwordx2 v[50:51], v[10:11], off offset:-4096
	global_load_dwordx2 v[52:53], v[10:11], off
	v_add_co_u32_e32 v10, vcc, 0x5000, v4
	v_and_b32_e32 v20, 63, v0
	s_nop 0
	v_addc_co_u32_e32 v11, vcc, 0, v5, vcc
	global_load_dwordx2 v[54:55], v[4:5], off
	global_load_dwordx2 v[56:57], v[6:7], off
	global_load_dwordx2 v[58:59], v[8:9], off
	global_load_dwordx2 v[60:61], v[10:11], off
	v_add_co_u32_e32 v6, vcc, s6, v4
	s_mov_b32 s6, 0xc000
	s_nop 0
	v_addc_co_u32_e32 v7, vcc, 0, v5, vcc
	v_add_co_u32_e32 v8, vcc, 0x7000, v4
	v_lshlrev_b32_e32 v21, 4, v20
	s_nop 0
	v_addc_co_u32_e32 v9, vcc, 0, v5, vcc
	v_add_co_u32_e32 v10, vcc, 0x8000, v4
	v_lshl_add_u32 v122, v0, 3, 0
	s_nop 0
	v_addc_co_u32_e32 v11, vcc, 0, v5, vcc
	v_add_co_u32_e32 v12, vcc, 0x9000, v4
	v_ashrrev_i32_e32 v22, 5, v0
	s_nop 0
	v_addc_co_u32_e32 v13, vcc, 0, v5, vcc
	global_load_dwordx2 v[62:63], v[6:7], off
	global_load_dwordx2 v[64:65], v[8:9], off
	global_load_dwordx2 v[66:67], v[10:11], off
	global_load_dwordx2 v[68:69], v[12:13], off
	v_add_co_u32_e32 v6, vcc, 0xa000, v4
	v_writelane_b32 v255, s68, 6
	s_nop 0
	v_addc_co_u32_e32 v7, vcc, 0, v5, vcc
	v_add_co_u32_e32 v8, vcc, 0xb000, v4
	v_lshl_add_u64 v[18:19], v[18:19], 1, s[0:1]
	s_nop 0
	v_addc_co_u32_e32 v9, vcc, 0, v5, vcc
	v_add_co_u32_e32 v10, vcc, s6, v4
	s_add_u32 s6, s4, s8
	s_nop 0
	v_addc_co_u32_e32 v11, vcc, 0, v5, vcc
	v_add_co_u32_e32 v12, vcc, 0xd000, v4
	s_addc_u32 s7, s3, s9
	s_nop 0
	v_addc_co_u32_e32 v13, vcc, 0, v5, vcc
	global_load_dwordx2 v[70:71], v[6:7], off
	global_load_dwordx2 v[72:73], v[8:9], off
	global_load_dwordx2 v[74:75], v[10:11], off
	global_load_dwordx2 v[76:77], v[12:13], off
	v_add_co_u32_e32 v6, vcc, 0xe000, v4
	s_add_u32 s4, s5, s8
	s_nop 0
	v_addc_co_u32_e32 v7, vcc, 0, v5, vcc
	v_add_co_u32_e32 v8, vcc, 0xf000, v4
	s_addc_u32 s5, s2, s9
	s_nop 0
	v_addc_co_u32_e32 v9, vcc, 0, v5, vcc
	v_add_co_u32_e32 v10, vcc, 0x10000, v4
	v_lshl_add_u64 v[2:3], s[6:7], 0, v[2:3]
	s_nop 0
	v_addc_co_u32_e32 v11, vcc, 0, v5, vcc
	v_add_co_u32_e32 v12, vcc, 0x11000, v4
	s_mov_b64 s[2:3], 0x4400000
	s_nop 0
	v_addc_co_u32_e32 v13, vcc, 0, v5, vcc
	global_load_dwordx2 v[78:79], v[6:7], off
	global_load_dwordx2 v[80:81], v[8:9], off
	global_load_dwordx2 v[82:83], v[10:11], off
	global_load_dwordx2 v[84:85], v[12:13], off
	v_add_co_u32_e32 v6, vcc, 0x12000, v4
	v_writelane_b32 v255, s76, 7
	s_nop 0
	v_addc_co_u32_e32 v7, vcc, 0, v5, vcc
	v_add_co_u32_e32 v8, vcc, 0x13000, v4
	v_lshl_add_u64 v[114:115], v[18:19], 0, s[2:3]
	s_nop 0
	v_addc_co_u32_e32 v9, vcc, 0, v5, vcc
	v_add_co_u32_e32 v10, vcc, 0x14000, v4
	v_and_b32_e32 v123, -2, v22
	s_nop 0
	v_addc_co_u32_e32 v11, vcc, 0, v5, vcc
	v_add_co_u32_e32 v12, vcc, 0x15000, v4
	v_or_b32_e32 v130, 1, v22
	s_nop 0
	v_addc_co_u32_e32 v13, vcc, 0, v5, vcc
	global_load_dwordx2 v[86:87], v[6:7], off
	global_load_dwordx2 v[88:89], v[8:9], off
	global_load_dwordx2 v[90:91], v[10:11], off
	global_load_dwordx2 v[92:93], v[12:13], off
	v_add_co_u32_e32 v6, vcc, 0x16000, v4
	v_writelane_b32 v255, s77, 8
	s_nop 0
	v_addc_co_u32_e32 v7, vcc, 0, v5, vcc
	v_add_co_u32_e32 v8, vcc, 0x17000, v4
	v_writelane_b32 v255, s26, 9
	s_nop 0
	v_addc_co_u32_e32 v9, vcc, 0, v5, vcc
	v_add_co_u32_e32 v10, vcc, 0x18000, v4
	s_mov_b32 s94, s88
	s_nop 0
	v_addc_co_u32_e32 v11, vcc, 0, v5, vcc
	v_add_co_u32_e32 v12, vcc, 0x19000, v4
	s_nop 1
	v_addc_co_u32_e32 v13, vcc, 0, v5, vcc
	global_load_dwordx2 v[94:95], v[6:7], off
	global_load_dwordx2 v[96:97], v[8:9], off
	global_load_dwordx2 v[98:99], v[10:11], off
	global_load_dwordx2 v[100:101], v[12:13], off
	v_add_co_u32_e32 v6, vcc, 0x1a000, v4
	s_nop 1
	v_addc_co_u32_e32 v7, vcc, 0, v5, vcc
	v_add_co_u32_e32 v8, vcc, 0x1b000, v4
	s_nop 1
	v_addc_co_u32_e32 v9, vcc, 0, v5, vcc
	v_add_co_u32_e32 v10, vcc, 0x1c000, v4
	s_nop 1
	v_addc_co_u32_e32 v11, vcc, 0, v5, vcc
	v_add_co_u32_e32 v12, vcc, 0x1d000, v4
	s_nop 1
	v_addc_co_u32_e32 v13, vcc, 0, v5, vcc
	v_add_co_u32_e32 v4, vcc, 0x1e000, v4
	global_load_dwordx2 v[102:103], v[6:7], off
	global_load_dwordx2 v[104:105], v[8:9], off
	global_load_dwordx2 v[106:107], v[10:11], off
	global_load_dwordx2 v[108:109], v[12:13], off
	v_addc_co_u32_e32 v5, vcc, 0, v5, vcc
	global_load_dwordx2 v[110:111], v[4:5], off
	global_load_dwordx2 v[112:113], v[2:3], off
	s_nop 0
	global_load_dwordx4 v[2:5], v21, s[4:5]
	global_load_dwordx4 v[6:9], v21, s[4:5] offset:1024
	global_load_dwordx4 v[10:13], v21, s[4:5] offset:2048
	global_load_dwordx4 v[14:17], v21, s[4:5] offset:3072
	v_cmp_lt_i32_e32 vcc, v191, v190
	v_add_u32_e32 v21, 0, v21
	s_nop 0
	v_cndmask_b32_e32 v0, v179, v191, vcc
	v_cmp_lt_i32_e32 vcc, v192, v190
	v_lshlrev_b32_e32 v124, 2, v0
	s_nop 0
	v_cndmask_b32_e32 v0, v179, v192, vcc
	v_cmp_lt_i32_e32 vcc, v193, v190
	v_lshlrev_b32_e32 v125, 2, v0
	s_nop 0
	v_cndmask_b32_e32 v0, v179, v193, vcc
	v_cmp_lt_i32_e32 vcc, v194, v190
	v_lshlrev_b32_e32 v126, 2, v0
	s_nop 0
	v_cndmask_b32_e32 v0, v179, v194, vcc
	v_cmp_lt_i32_e32 vcc, v195, v190
	v_lshlrev_b32_e32 v127, 2, v0
	s_nop 0
	v_cndmask_b32_e32 v0, v179, v195, vcc
	v_cmp_lt_i32_e32 vcc, v196, v190
	v_lshlrev_b32_e32 v128, 2, v0
	s_nop 0
	v_cndmask_b32_e32 v0, v179, v196, vcc
	v_lshlrev_b32_e32 v129, 2, v0
	v_lshlrev_b32_e32 v0, 3, v20
	v_lshl_add_u64 v[18:19], s[0:1], 0, v[0:1]
	s_mov_b64 s[0:1], 0x6500000
	v_lshl_add_u64 v[116:117], v[18:19], 0, s[0:1]
	v_lshlrev_b32_e32 v0, 12, v123
	v_lshlrev_b32_e32 v18, 12, v130
	v_readlane_b32 s0, v253, 2
	v_add_u32_e32 v131, v21, v0
	v_add_u32_e32 v132, v21, v18
	s_mov_b32 s2, s0
	v_writelane_b32 v255, 0, 22
.LBB0_501:
	s_sub_i32 s3, s94, 1
	s_cmpk_lt_u32 s3, 0x3fe
	s_cbranch_scc1 .Ldw_fast
	s_sub_i32 s3, s94, 0x401
	s_cmp_lt_u32 s3, 14
	s_cbranch_scc1 .Ldw_fast
	s_cmpk_lt_i32 s94, 0x400
	s_cselect_b32 s89, 0, 0x4000
	s_cselect_b32 s88, s86, 0x4100
	s_add_i32 s3, s2, -15
	s_cmp_ge_i32 s3, s89
	s_cselect_b64 s[0:1], -1, 0
	s_cmp_lt_i32 s3, s88
	s_cselect_b64 s[4:5], -1, 0
	s_and_b64 s[0:1], s[0:1], s[4:5]
	s_and_b64 s[4:5], s[0:1], exec
	s_cselect_b32 s4, s3, s2
	s_ashr_i32 s5, s4, 31
	s_lshl_b64 s[4:5], s[4:5], 11
	s_add_i32 s3, s2, -14
	s_cmp_ge_i32 s3, s89
	v_lshl_add_u64 v[18:19], v[114:115], 0, s[4:5]
	s_cselect_b64 s[4:5], -1, 0
	s_cmp_lt_i32 s3, s88
	s_cselect_b64 s[6:7], -1, 0
	s_and_b64 s[6:7], s[4:5], s[6:7]
	s_and_b64 s[4:5], s[6:7], exec
	s_cselect_b32 s4, s3, s2
	s_ashr_i32 s5, s4, 31
	s_lshl_b64 s[4:5], s[4:5], 11
	s_add_i32 s3, s2, -13
	s_cmp_ge_i32 s3, s89
	global_load_dword v0, v[18:19], off
	v_lshl_add_u64 v[18:19], v[114:115], 0, s[4:5]
	s_cselect_b64 s[4:5], -1, 0
	s_cmp_lt_i32 s3, s88
	s_cselect_b64 s[8:9], -1, 0
	s_and_b64 s[12:13], s[4:5], s[8:9]
	s_and_b64 s[4:5], s[12:13], exec
	s_cselect_b32 s4, s3, s2
	s_ashr_i32 s5, s4, 31
	s_lshl_b64 s[4:5], s[4:5], 11
	s_add_i32 s3, s2, -12
	s_cmp_ge_i32 s3, s89
	v_lshl_add_u64 v[20:21], v[114:115], 0, s[4:5]
	s_cselect_b64 s[4:5], -1, 0
	s_cmp_lt_i32 s3, s88
	s_cselect_b64 s[8:9], -1, 0
	s_and_b64 s[30:31], s[4:5], s[8:9]
	s_and_b64 s[4:5], s[30:31], exec
	s_cselect_b32 s4, s3, s2
	s_ashr_i32 s5, s4, 31
	s_lshl_b64 s[4:5], s[4:5], 11
	s_add_i32 s3, s2, -11
	s_cmp_ge_i32 s3, s89
	v_lshl_add_u64 v[22:23], v[114:115], 0, s[4:5]
	s_cselect_b64 s[4:5], -1, 0
	s_cmp_lt_i32 s3, s88
	s_cselect_b64 s[8:9], -1, 0
	s_and_b64 s[36:37], s[4:5], s[8:9]
	s_and_b64 s[4:5], s[36:37], exec
	s_cselect_b32 s4, s3, s2
	s_ashr_i32 s5, s4, 31
	s_lshl_b64 s[4:5], s[4:5], 11
	s_add_i32 s3, s2, -10
	s_cmp_ge_i32 s3, s89
	global_load_dword v18, v[18:19], off
	s_mov_b32 s96, s70
	global_load_dword v21, v[20:21], off
	s_mov_b32 s97, s84
	global_load_dword v29, v[22:23], off
	v_lshl_add_u64 v[22:23], v[114:115], 0, s[4:5]
	s_cselect_b64 s[4:5], -1, 0
	s_cmp_lt_i32 s3, s88
	s_cselect_b64 s[8:9], -1, 0
	s_and_b64 s[50:51], s[4:5], s[8:9]
	s_and_b64 s[4:5], s[50:51], exec
	s_cselect_b32 s4, s3, s2
	s_ashr_i32 s5, s4, 31
	s_lshl_b64 s[4:5], s[4:5], 11
	s_add_i32 s3, s2, -9
	s_cmp_ge_i32 s3, s89
	global_load_dword v32, v[22:23], off
	v_lshl_add_u64 v[22:23], v[114:115], 0, s[4:5]
	s_cselect_b64 s[4:5], -1, 0
	s_cmp_lt_i32 s3, s88
	s_cselect_b64 s[8:9], -1, 0
	s_and_b64 s[58:59], s[4:5], s[8:9]
	s_and_b64 s[4:5], s[58:59], exec
	s_cselect_b32 s4, s3, s2
	s_ashr_i32 s5, s4, 31
	s_lshl_b64 s[4:5], s[4:5], 11
	s_add_i32 s3, s2, -8
	s_cmp_gt_i32 s2, s89
	global_load_dword v38, v[22:23], off
	v_lshl_add_u64 v[22:23], v[114:115], 0, s[4:5]
	s_cselect_b64 s[4:5], -1, 0
	s_cmp_le_i32 s2, s88
	s_cselect_b64 s[8:9], -1, 0
	s_and_b64 vcc, s[4:5], s[8:9]
	s_and_b64 s[4:5], vcc, exec
	s_cselect_b32 s4, s3, s2
	s_ashr_i32 s5, s4, 31
	s_lshl_b64 s[4:5], s[4:5], 11
	s_add_i32 s3, s2, -7
	s_cmp_ge_i32 s3, s89
	global_load_dword v43, v[22:23], off
	v_lshl_add_u64 v[22:23], v[114:115], 0, s[4:5]
	s_cselect_b64 s[4:5], -1, 0
	s_cmp_lt_i32 s3, s88
	s_cselect_b64 s[8:9], -1, 0
	s_and_b64 s[70:71], s[4:5], s[8:9]
	s_and_b64 s[4:5], s[70:71], exec
	s_cselect_b32 s4, s3, s2
	s_ashr_i32 s5, s4, 31
	s_lshl_b64 s[4:5], s[4:5], 11
	s_add_i32 s3, s2, -6
	s_cmp_ge_i32 s3, s89
	global_load_dword v119, v[22:23], off
	v_lshl_add_u64 v[22:23], v[114:115], 0, s[4:5]
	s_cselect_b64 s[4:5], -1, 0
	s_cmp_lt_i32 s3, s88
	s_cselect_b64 s[8:9], -1, 0
	s_and_b64 s[76:77], s[4:5], s[8:9]
	s_and_b64 s[4:5], s[76:77], exec
	s_cselect_b32 s4, s3, s2
	s_ashr_i32 s5, s4, 31
	s_lshl_b64 s[4:5], s[4:5], 11
	s_add_i32 s3, s2, -5
	s_cmp_ge_i32 s3, s89
	global_load_dword v134, v[22:23], off
	v_lshl_add_u64 v[22:23], v[114:115], 0, s[4:5]
	s_cselect_b64 s[4:5], -1, 0
	s_cmp_lt_i32 s3, s88
	s_cselect_b64 s[8:9], -1, 0
	s_and_b64 s[78:79], s[4:5], s[8:9]
	s_and_b64 s[4:5], s[78:79], exec
	s_cselect_b32 s4, s3, s2
	s_ashr_i32 s5, s4, 31
	s_lshl_b64 s[4:5], s[4:5], 11
	s_add_i32 s3, s2, -4
	global_load_dword v137, v[22:23], off
	v_lshl_add_u64 v[22:23], v[114:115], 0, s[4:5]
	s_and_b64 s[4:5], vcc, exec
	s_cselect_b32 s4, s3, s2
	s_ashr_i32 s5, s4, 31
	s_lshl_b64 s[4:5], s[4:5], 11
	s_add_i32 s3, s2, -3
	s_cmp_ge_i32 s3, s89
	global_load_dword v138, v[22:23], off
	v_lshl_add_u64 v[22:23], v[114:115], 0, s[4:5]
	s_cselect_b64 s[4:5], -1, 0
	s_cmp_lt_i32 s3, s88
	s_cselect_b64 s[8:9], -1, 0
	s_and_b64 s[74:75], s[4:5], s[8:9]
	s_and_b64 s[4:5], s[74:75], exec
	s_cselect_b32 s4, s3, s2
	s_ashr_i32 s5, s4, 31
	s_lshl_b64 s[4:5], s[4:5], 11
	s_add_i32 s3, s2, -2
	global_load_dword v135, v[22:23], off
	v_lshl_add_u64 v[22:23], v[114:115], 0, s[4:5]
	s_and_b64 s[4:5], vcc, exec
	s_cselect_b32 s4, s3, s2
	s_ashr_i32 s5, s4, 31
	s_lshl_b64 s[4:5], s[4:5], 11
	s_cmp_lg_u64 vcc, 0
	global_load_dword v136, v[22:23], off
	v_lshl_add_u64 v[22:23], v[114:115], 0, s[4:5]
	s_subb_u32 s4, s2, 0
	s_ashr_i32 s5, s4, 31
	s_lshl_b64 s[4:5], s[4:5], 11
	s_ashr_i32 s3, s2, 31
	global_load_dword v121, v[22:23], off
	v_lshl_add_u64 v[22:23], v[114:115], 0, s[4:5]
	s_lshl_b64 s[4:5], s[2:3], 11
	s_add_i32 s3, s2, 1
	s_cmp_ge_i32 s3, s89
	global_load_dword v49, v[22:23], off
	v_lshl_add_u64 v[22:23], v[114:115], 0, s[4:5]
	s_cselect_b64 s[4:5], -1, 0
	s_cmp_lt_i32 s3, s88
	s_cselect_b64 s[8:9], -1, 0
	s_and_b64 s[64:65], s[4:5], s[8:9]
	s_and_b64 s[4:5], s[64:65], exec
	s_cselect_b32 s4, s3, s2
	s_ashr_i32 s5, s4, 31
	s_lshl_b64 s[4:5], s[4:5], 11
	s_add_i32 s3, s2, 2
	s_cmp_ge_i32 s3, s89
	global_load_dword v47, v[22:23], off
	v_lshl_add_u64 v[22:23], v[114:115], 0, s[4:5]
	s_cselect_b64 s[4:5], -1, 0
	s_cmp_lt_i32 s3, s88
	s_cselect_b64 s[8:9], -1, 0
	s_and_b64 s[62:63], s[4:5], s[8:9]
	s_and_b64 s[4:5], s[62:63], exec
	s_cselect_b32 s4, s3, s2
	s_ashr_i32 s5, s4, 31
	s_lshl_b64 s[4:5], s[4:5], 11
	s_add_i32 s3, s2, 3
	s_cmp_ge_i32 s3, s89
	global_load_dword v48, v[22:23], off
	v_lshl_add_u64 v[22:23], v[114:115], 0, s[4:5]
	s_cselect_b64 s[4:5], -1, 0
	s_cmp_lt_i32 s3, s88
	s_cselect_b64 s[8:9], -1, 0
	s_and_b64 s[60:61], s[4:5], s[8:9]
	s_and_b64 s[4:5], s[60:61], exec
	s_cselect_b32 s4, s3, s2
	s_ashr_i32 s5, s4, 31
	s_lshl_b64 s[4:5], s[4:5], 11
	s_add_i32 s3, s2, 4
	s_cmp_ge_i32 s3, s89
	global_load_dword v46, v[22:23], off
	v_lshl_add_u64 v[22:23], v[114:115], 0, s[4:5]
	s_cselect_b64 s[4:5], -1, 0
	s_cmp_lt_i32 s3, s88
	s_cselect_b64 s[8:9], -1, 0
	s_and_b64 s[56:57], s[4:5], s[8:9]
	s_and_b64 s[4:5], s[56:57], exec
	s_cselect_b32 s4, s3, s2
	s_ashr_i32 s5, s4, 31
	s_lshl_b64 s[4:5], s[4:5], 11
	s_add_i32 s3, s2, 5
	s_cmp_ge_i32 s3, s89
	global_load_dword v44, v[22:23], off
	v_lshl_add_u64 v[22:23], v[114:115], 0, s[4:5]
	s_cselect_b64 s[4:5], -1, 0
	s_cmp_lt_i32 s3, s88
	s_cselect_b64 s[8:9], -1, 0
	s_and_b64 s[52:53], s[4:5], s[8:9]
	s_and_b64 s[4:5], s[52:53], exec
	s_cselect_b32 s4, s3, s2
	s_ashr_i32 s5, s4, 31
	s_lshl_b64 s[4:5], s[4:5], 11
	s_add_i32 s3, s2, 6
	s_cmp_ge_i32 s3, s89
	global_load_dword v42, v[22:23], off
	v_lshl_add_u64 v[22:23], v[114:115], 0, s[4:5]
	s_cselect_b64 s[4:5], -1, 0
	s_cmp_lt_i32 s3, s88
	s_cselect_b64 s[8:9], -1, 0
	s_and_b64 s[44:45], s[4:5], s[8:9]
	s_and_b64 s[4:5], s[44:45], exec
	s_cselect_b32 s4, s3, s2
	s_ashr_i32 s5, s4, 31
	s_lshl_b64 s[4:5], s[4:5], 11
	s_add_i32 s3, s2, 7
	s_cmp_ge_i32 s3, s89
	global_load_dword v39, v[22:23], off
	v_lshl_add_u64 v[22:23], v[114:115], 0, s[4:5]
	s_cselect_b64 s[4:5], -1, 0
	s_cmp_lt_i32 s3, s88
	s_cselect_b64 s[8:9], -1, 0
	s_and_b64 s[38:39], s[4:5], s[8:9]
	s_and_b64 s[4:5], s[38:39], exec
	s_cselect_b32 s4, s3, s2
	s_ashr_i32 s5, s4, 31
	s_lshl_b64 s[4:5], s[4:5], 11
	s_add_i32 s3, s2, 8
	s_cmp_ge_i32 s3, s89
	global_load_dword v36, v[22:23], off
	v_lshl_add_u64 v[22:23], v[114:115], 0, s[4:5]
	s_cselect_b64 s[4:5], -1, 0
	s_cmp_lt_i32 s3, s88
	s_cselect_b64 s[8:9], -1, 0
	s_and_b64 s[24:25], s[4:5], s[8:9]
	s_and_b64 s[4:5], s[24:25], exec
	s_cselect_b32 s4, s3, s2
	s_ashr_i32 s5, s4, 31
	s_lshl_b64 s[4:5], s[4:5], 11
	s_add_i32 s3, s2, 9
	s_cmp_ge_i32 s3, s89
	global_load_dword v33, v[22:23], off
	v_lshl_add_u64 v[22:23], v[114:115], 0, s[4:5]
	s_cselect_b64 s[4:5], -1, 0
	s_cmp_lt_i32 s3, s88
	s_cselect_b64 s[8:9], -1, 0
	s_and_b64 s[54:55], s[4:5], s[8:9]
	s_and_b64 s[4:5], s[54:55], exec
	s_cselect_b32 s4, s3, s2
	s_ashr_i32 s5, s4, 31
	s_lshl_b64 s[4:5], s[4:5], 11
	s_add_i32 s3, s2, 10
	s_cmp_ge_i32 s3, s89
	global_load_dword v40, v[22:23], off
	v_lshl_add_u64 v[22:23], v[114:115], 0, s[4:5]
	s_cselect_b64 s[4:5], -1, 0
	s_cmp_lt_i32 s3, s88
	s_cselect_b64 s[8:9], -1, 0
	s_and_b64 s[48:49], s[4:5], s[8:9]
	s_and_b64 s[4:5], s[48:49], exec
	s_cselect_b32 s4, s3, s2
	s_ashr_i32 s5, s4, 31
	s_lshl_b64 s[4:5], s[4:5], 11
	s_add_i32 s3, s2, 11
	s_cmp_ge_i32 s3, s89
	global_load_dword v41, v[22:23], off
	v_lshl_add_u64 v[22:23], v[114:115], 0, s[4:5]
	s_cselect_b64 s[4:5], -1, 0
	s_cmp_lt_i32 s3, s88
	s_cselect_b64 s[8:9], -1, 0
	s_and_b64 s[42:43], s[4:5], s[8:9]
	s_and_b64 s[4:5], s[42:43], exec
	s_cselect_b32 s4, s3, s2
	s_ashr_i32 s5, s4, 31
	s_lshl_b64 s[4:5], s[4:5], 11
	s_add_i32 s3, s2, 12
	s_cmp_ge_i32 s3, s89
	global_load_dword v37, v[22:23], off
	v_lshl_add_u64 v[22:23], v[114:115], 0, s[4:5]
	s_cselect_b64 s[4:5], -1, 0
	s_cmp_lt_i32 s3, s88
	s_cselect_b64 s[8:9], -1, 0
	s_and_b64 s[34:35], s[4:5], s[8:9]
	s_and_b64 s[4:5], s[34:35], exec
	s_cselect_b32 s4, s3, s2
	s_ashr_i32 s5, s4, 31
	s_lshl_b64 s[4:5], s[4:5], 11
	s_add_i32 s3, s2, 13
	s_cmp_ge_i32 s3, s89
	global_load_dword v35, v[22:23], off
	v_lshl_add_u64 v[22:23], v[114:115], 0, s[4:5]
	s_cselect_b64 s[4:5], -1, 0
	s_cmp_lt_i32 s3, s88
	s_cselect_b64 s[8:9], -1, 0
	s_and_b64 s[14:15], s[4:5], s[8:9]
	s_and_b64 s[4:5], s[14:15], exec
	s_cselect_b32 s4, s3, s2
	s_ashr_i32 s5, s4, 31
	s_lshl_b64 s[4:5], s[4:5], 11
	s_add_i32 s3, s2, 14
	s_cmp_ge_i32 s3, s89
	global_load_dword v30, v[22:23], off
	v_lshl_add_u64 v[22:23], v[114:115], 0, s[4:5]
	s_cselect_b64 s[4:5], -1, 0
	s_cmp_lt_i32 s3, s88
	s_cselect_b64 s[8:9], -1, 0
	s_and_b64 s[10:11], s[4:5], s[8:9]
	s_and_b64 s[4:5], s[10:11], exec
	s_cselect_b32 s4, s3, s2
	s_ashr_i32 s5, s4, 31
	s_lshl_b64 s[4:5], s[4:5], 11
	s_add_i32 s3, s2, 15
	s_cmp_ge_i32 s3, s89
	v_lshl_add_u64 v[24:25], v[114:115], 0, s[4:5]
	s_cselect_b64 s[4:5], -1, 0
	s_cmp_lt_i32 s3, s88
	s_cselect_b64 s[8:9], -1, 0
	s_and_b64 s[8:9], s[4:5], s[8:9]
	s_and_b64 s[4:5], s[8:9], exec
	s_cselect_b32 s4, s3, s2
	s_ashr_i32 s5, s4, 31
	s_lshl_b64 s[4:5], s[4:5], 11
	s_add_i32 s3, s2, 16
	s_cmp_ge_i32 s3, s89
	global_load_dword v22, v[22:23], off
	s_nop 0
	global_load_dword v20, v[24:25], off
	v_lshl_add_u64 v[24:25], v[114:115], 0, s[4:5]
	s_cselect_b64 s[4:5], -1, 0
	s_cmp_lt_i32 s3, s88
	s_cselect_b64 s[16:17], -1, 0
	s_and_b64 s[4:5], s[4:5], s[16:17]
	s_and_b64 s[16:17], s[4:5], exec
	s_cselect_b32 s16, s3, s2
	s_ashr_i32 s17, s16, 31
	s_lshl_b64 s[16:17], s[16:17], 11
	s_add_i32 s3, s2, 17
	s_cmp_ge_i32 s3, s89
	global_load_dword v19, v[24:25], off
	v_lshl_add_u64 v[24:25], v[114:115], 0, s[16:17]
	s_cselect_b64 s[16:17], -1, 0
	s_cmp_lt_i32 s3, s88
	s_cselect_b64 s[18:19], -1, 0
	s_and_b64 s[26:27], s[16:17], s[18:19]
	s_and_b64 s[16:17], s[26:27], exec
	s_cselect_b32 s16, s3, s2
	s_ashr_i32 s17, s16, 31
	s_lshl_b64 s[16:17], s[16:17], 11
	s_add_i32 s3, s2, 18
	s_cmp_ge_i32 s3, s89
	global_load_dword v27, v[24:25], off
	v_lshl_add_u64 v[24:25], v[114:115], 0, s[16:17]
	s_cselect_b64 s[16:17], -1, 0
	s_cmp_lt_i32 s3, s88
	s_cselect_b64 s[18:19], -1, 0
	s_and_b64 s[20:21], s[16:17], s[18:19]
	s_and_b64 s[16:17], s[20:21], exec
	s_cselect_b32 s16, s3, s2
	s_ashr_i32 s17, s16, 31
	s_lshl_b64 s[16:17], s[16:17], 11
	s_add_i32 s3, s2, 19
	s_cmp_ge_i32 s3, s89
	global_load_dword v31, v[24:25], off
	v_lshl_add_u64 v[24:25], v[114:115], 0, s[16:17]
	s_cselect_b64 s[16:17], -1, 0
	s_cmp_lt_i32 s3, s88
	s_cselect_b64 s[18:19], -1, 0
	s_and_b64 s[16:17], s[16:17], s[18:19]
	s_and_b64 s[18:19], s[16:17], exec
	s_cselect_b32 s18, s3, s2
	s_ashr_i32 s19, s18, 31
	s_lshl_b64 s[18:19], s[18:19], 11
	s_add_i32 s3, s2, 20
	s_cmp_ge_i32 s3, s89
	v_lshl_add_u64 v[140:141], v[114:115], 0, s[18:19]
	s_cselect_b64 s[18:19], -1, 0
	s_cmp_lt_i32 s3, s88
	s_cselect_b64 s[22:23], -1, 0
	s_and_b64 s[18:19], s[18:19], s[22:23]
	s_and_b64 s[22:23], s[18:19], exec
	s_cselect_b32 s22, s3, s2
	s_ashr_i32 s23, s22, 31
	s_lshl_b64 s[22:23], s[22:23], 11
	s_add_i32 s3, s2, 21
	s_cmp_ge_i32 s3, s89
	global_load_dword v25, v[24:25], off
	s_nop 0
	global_load_dword v23, v[140:141], off
	v_lshl_add_u64 v[140:141], v[114:115], 0, s[22:23]
	s_cselect_b64 s[22:23], -1, 0
	s_cmp_lt_i32 s3, s88
	s_cselect_b64 s[28:29], -1, 0
	s_and_b64 s[22:23], s[22:23], s[28:29]
	s_and_b64 s[28:29], s[22:23], exec
	s_cselect_b32 s28, s3, s2
	s_ashr_i32 s29, s28, 31
	s_lshl_b64 s[28:29], s[28:29], 11
	s_add_i32 s3, s2, 22
	s_cmp_ge_i32 s3, s89
	global_load_dword v24, v[140:141], off
	v_lshl_add_u64 v[140:141], v[114:115], 0, s[28:29]
	s_cselect_b64 s[28:29], -1, 0
	s_cmp_lt_i32 s3, s88
	s_cselect_b64 s[40:41], -1, 0
	s_and_b64 s[28:29], s[28:29], s[40:41]
	s_and_b64 s[40:41], s[28:29], exec
	s_cselect_b32 s40, s3, s2
	s_ashr_i32 s41, s40, 31
	s_lshl_b64 s[40:41], s[40:41], 11
	s_add_i32 s3, s2, 23
	s_cmp_ge_i32 s3, s89
	global_load_dword v26, v[140:141], off
	v_lshl_add_u64 v[140:141], v[114:115], 0, s[40:41]
	s_cselect_b64 s[40:41], -1, 0
	s_cmp_lt_i32 s3, s88
	s_cselect_b64 s[46:47], -1, 0
	s_and_b64 s[40:41], s[40:41], s[46:47]
	s_and_b64 s[46:47], s[40:41], exec
	s_cselect_b32 s46, s3, s2
	s_ashr_i32 s47, s46, 31
	s_lshl_b64 s[46:47], s[46:47], 11
	s_add_i32 s3, s2, 24
	s_cmp_ge_i32 s3, s89
	global_load_dword v28, v[140:141], off
	v_lshl_add_u64 v[140:141], v[114:115], 0, s[46:47]
	s_cselect_b64 s[46:47], -1, 0
	s_cmp_lt_i32 s3, s88
	s_cselect_b64 s[66:67], -1, 0
	s_and_b64 s[46:47], s[46:47], s[66:67]
	s_and_b64 s[66:67], s[46:47], exec
	s_cselect_b32 s66, s3, s2
	s_ashr_i32 s67, s66, 31
	s_lshl_b64 s[66:67], s[66:67], 11
	s_add_i32 s3, s2, 25
	s_cmp_ge_i32 s3, s89
	global_load_dword v34, v[140:141], off
	v_lshl_add_u64 v[140:141], v[114:115], 0, s[66:67]
	s_cselect_b64 s[66:67], -1, 0
	s_cmp_lt_i32 s3, s88
	s_cselect_b64 s[68:69], -1, 0
	s_and_b64 s[66:67], s[66:67], s[68:69]
	s_and_b64 s[68:69], s[66:67], exec
	s_cselect_b32 s68, s3, s2
	s_ashr_i32 s69, s68, 31
	s_lshl_b64 s[68:69], s[68:69], 11
	s_add_i32 s3, s2, 26
	s_cmp_ge_i32 s3, s89
	global_load_dword v45, v[140:141], off
	v_lshl_add_u64 v[140:141], v[114:115], 0, s[68:69]
	s_cselect_b64 s[68:69], -1, 0
	s_cmp_lt_i32 s3, s88
	s_cselect_b64 s[72:73], -1, 0
	s_and_b64 s[68:69], s[68:69], s[72:73]
	s_and_b64 s[72:73], s[68:69], exec
	s_cselect_b32 s72, s3, s2
	s_ashr_i32 s73, s72, 31
	s_lshl_b64 s[72:73], s[72:73], 11
	s_add_i32 s3, s2, 27
	s_cmp_ge_i32 s3, s89
	global_load_dword v118, v[140:141], off
	v_lshl_add_u64 v[140:141], v[114:115], 0, s[72:73]
	s_cselect_b64 s[72:73], -1, 0
	s_cmp_lt_i32 s3, s88
	s_cselect_b64 s[80:81], -1, 0
	s_and_b64 s[72:73], s[72:73], s[80:81]
	s_and_b64 s[80:81], s[72:73], exec
	s_cselect_b32 s80, s3, s2
	s_ashr_i32 s81, s80, 31
	s_lshl_b64 s[80:81], s[80:81], 11
	s_add_i32 s3, s2, 28
	s_cmp_ge_i32 s3, s89
	global_load_dword v120, v[140:141], off
	v_lshl_add_u64 v[140:141], v[114:115], 0, s[80:81]
	s_cselect_b64 s[80:81], -1, 0
	s_cmp_lt_i32 s3, s88
	s_cselect_b64 s[82:83], -1, 0
	s_and_b64 s[80:81], s[80:81], s[82:83]
	s_and_b64 s[82:83], s[80:81], exec
	s_cselect_b32 s82, s3, s2
	s_ashr_i32 s83, s82, 31
	s_lshl_b64 s[82:83], s[82:83], 11
	s_add_i32 s3, s2, 29
	s_cmp_ge_i32 s3, s89
	global_load_dword v133, v[140:141], off
	v_lshl_add_u64 v[140:141], v[114:115], 0, s[82:83]
	s_cselect_b64 s[82:83], -1, 0
	s_cmp_lt_i32 s3, s88
	s_cselect_b64 s[84:85], -1, 0
	s_and_b64 s[82:83], s[82:83], s[84:85]
	s_and_b64 s[84:85], s[82:83], exec
	s_cselect_b32 s84, s3, s2
	s_ashr_i32 s85, s84, 31
	s_lshl_b64 s[84:85], s[84:85], 11
	s_add_i32 s3, s2, 30
	s_cmp_ge_i32 s3, s89
	global_load_dword v139, v[140:141], off
	v_lshl_add_u64 v[140:141], v[114:115], 0, s[84:85]
	s_cselect_b64 s[84:85], -1, 0
	s_cmp_lt_i32 s3, s88
	s_cselect_b64 s[86:87], -1, 0
	s_and_b64 s[84:85], s[84:85], s[86:87]
	s_and_b64 s[86:87], s[84:85], exec
	s_cselect_b32 s86, s3, s2
	s_ashr_i32 s87, s86, 31
	s_lshl_b64 s[86:87], s[86:87], 11
	v_lshl_add_u64 v[142:143], v[114:115], 0, s[86:87]
	global_load_dword v140, v[140:141], off
	s_movk_i32 s86, 0x4000
	global_load_dword v141, v[142:143], off
	s_waitcnt vmcnt(45)
	v_lshlrev_b32_e32 v142, 16, v0
	v_and_b32_e32 v0, 0xffff0000, v0
	v_cndmask_b32_e64 v143, 0, v0, s[0:1]
	s_waitcnt vmcnt(44)
	v_lshlrev_b32_e32 v0, 16, v18
	v_cndmask_b32_e64 v144, 0, v0, s[6:7]
	v_and_b32_e32 v0, 0xffff0000, v18
	v_cndmask_b32_e64 v145, 0, v0, s[6:7]
	s_waitcnt vmcnt(43)
	v_lshlrev_b32_e32 v0, 16, v21
	v_cndmask_b32_e64 v146, 0, v0, s[12:13]
	v_and_b32_e32 v0, 0xffff0000, v21
	v_cndmask_b32_e64 v147, 0, v0, s[12:13]
	s_waitcnt vmcnt(42)
	v_lshlrev_b32_e32 v0, 16, v29
	v_cndmask_b32_e64 v148, 0, v0, s[30:31]
	v_and_b32_e32 v0, 0xffff0000, v29
	v_cndmask_b32_e64 v149, 0, v0, s[30:31]
	s_waitcnt vmcnt(41)
	v_lshlrev_b32_e32 v0, 16, v32
	v_cndmask_b32_e64 v152, 0, v0, s[36:37]
	v_and_b32_e32 v0, 0xffff0000, v32
	v_cndmask_b32_e64 v153, 0, v0, s[36:37]
	s_waitcnt vmcnt(40)
	v_lshlrev_b32_e32 v0, 16, v38
	v_cndmask_b32_e64 v154, 0, v0, s[50:51]
	v_and_b32_e32 v0, 0xffff0000, v38
	v_cndmask_b32_e64 v155, 0, v0, s[50:51]
	s_waitcnt vmcnt(39)
	v_lshlrev_b32_e32 v0, 16, v43
	v_cndmask_b32_e64 v156, 0, v0, s[58:59]
	v_and_b32_e32 v0, 0xffff0000, v43
	v_cndmask_b32_e64 v142, 0, v142, s[0:1]
	v_cndmask_b32_e64 v157, 0, v0, s[58:59]
	s_waitcnt vmcnt(38)
	v_lshlrev_b32_e32 v0, 16, v119
	v_pk_fma_f32 v[142:143], v[54:55], v[142:143], v[112:113]
	v_cndmask_b32_e32 v158, 0, v0, vcc
	v_and_b32_e32 v0, 0xffff0000, v119
	v_pk_fma_f32 v[142:143], v[56:57], v[144:145], v[142:143]
	v_pk_fma_f32 v[144:145], v[54:55], v[144:145], v[112:113]
	v_cndmask_b32_e32 v159, 0, v0, vcc
	s_waitcnt vmcnt(37)
	v_lshlrev_b32_e32 v0, 16, v134
	v_pk_fma_f32 v[142:143], v[58:59], v[146:147], v[142:143]
	v_pk_fma_f32 v[144:145], v[56:57], v[146:147], v[144:145]
	v_pk_fma_f32 v[146:147], v[54:55], v[146:147], v[112:113]
	v_cndmask_b32_e64 v160, 0, v0, s[70:71]
	v_and_b32_e32 v0, 0xffff0000, v134
	v_pk_fma_f32 v[142:143], v[50:51], v[148:149], v[142:143]
	v_pk_fma_f32 v[144:145], v[58:59], v[148:149], v[144:145]
	v_pk_fma_f32 v[146:147], v[56:57], v[148:149], v[146:147]
	v_pk_fma_f32 v[148:149], v[54:55], v[148:149], v[112:113]
	v_cndmask_b32_e64 v161, 0, v0, s[70:71]
	s_waitcnt vmcnt(36)
	v_lshlrev_b32_e32 v0, 16, v137
	v_pk_fma_f32 v[142:143], v[52:53], v[152:153], v[142:143]
	v_pk_fma_f32 v[144:145], v[50:51], v[152:153], v[144:145]
	v_pk_fma_f32 v[146:147], v[58:59], v[152:153], v[146:147]
	v_pk_fma_f32 v[148:149], v[56:57], v[152:153], v[148:149]
	v_pk_fma_f32 v[152:153], v[54:55], v[152:153], v[112:113]
	v_cndmask_b32_e64 v162, 0, v0, s[76:77]
	v_and_b32_e32 v0, 0xffff0000, v137
	v_pk_fma_f32 v[142:143], v[60:61], v[154:155], v[142:143]
	v_pk_fma_f32 v[144:145], v[52:53], v[154:155], v[144:145]
	v_pk_fma_f32 v[146:147], v[50:51], v[154:155], v[146:147]
	v_pk_fma_f32 v[148:149], v[58:59], v[154:155], v[148:149]
	v_pk_fma_f32 v[152:153], v[56:57], v[154:155], v[152:153]
	v_pk_fma_f32 v[154:155], v[54:55], v[154:155], v[112:113]
	v_cndmask_b32_e64 v163, 0, v0, s[76:77]
	s_waitcnt vmcnt(35)
	v_lshlrev_b32_e32 v0, 16, v138
	v_pk_fma_f32 v[142:143], v[62:63], v[156:157], v[142:143]
	v_pk_fma_f32 v[144:145], v[60:61], v[156:157], v[144:145]
	v_pk_fma_f32 v[146:147], v[52:53], v[156:157], v[146:147]
	v_pk_fma_f32 v[148:149], v[50:51], v[156:157], v[148:149]
	v_pk_fma_f32 v[152:153], v[58:59], v[156:157], v[152:153]
	v_pk_fma_f32 v[154:155], v[56:57], v[156:157], v[154:155]
	v_pk_fma_f32 v[156:157], v[54:55], v[156:157], v[112:113]
	v_cndmask_b32_e64 v164, 0, v0, s[78:79]
	v_and_b32_e32 v0, 0xffff0000, v138
	v_pk_fma_f32 v[142:143], v[64:65], v[158:159], v[142:143]
	v_pk_fma_f32 v[144:145], v[62:63], v[158:159], v[144:145]
	v_pk_fma_f32 v[146:147], v[60:61], v[158:159], v[146:147]
	v_pk_fma_f32 v[148:149], v[52:53], v[158:159], v[148:149]
	v_pk_fma_f32 v[152:153], v[50:51], v[158:159], v[152:153]
	v_pk_fma_f32 v[154:155], v[58:59], v[158:159], v[154:155]
	v_pk_fma_f32 v[156:157], v[56:57], v[158:159], v[156:157]
	v_pk_fma_f32 v[158:159], v[54:55], v[158:159], v[112:113]
	v_cndmask_b32_e64 v165, 0, v0, s[78:79]
	s_waitcnt vmcnt(34)
	v_lshlrev_b32_e32 v0, 16, v135
	v_pk_fma_f32 v[142:143], v[66:67], v[160:161], v[142:143]
	v_pk_fma_f32 v[144:145], v[64:65], v[160:161], v[144:145]
	v_pk_fma_f32 v[146:147], v[62:63], v[160:161], v[146:147]
	v_pk_fma_f32 v[148:149], v[60:61], v[160:161], v[148:149]
	v_pk_fma_f32 v[152:153], v[52:53], v[160:161], v[152:153]
	v_pk_fma_f32 v[154:155], v[50:51], v[160:161], v[154:155]
	v_pk_fma_f32 v[156:157], v[58:59], v[160:161], v[156:157]
	v_pk_fma_f32 v[158:159], v[56:57], v[160:161], v[158:159]
	v_pk_fma_f32 v[160:161], v[54:55], v[160:161], v[112:113]
	v_cndmask_b32_e32 v134, 0, v0, vcc
	v_and_b32_e32 v0, 0xffff0000, v135
	v_pk_fma_f32 v[142:143], v[68:69], v[162:163], v[142:143]
	v_pk_fma_f32 v[144:145], v[66:67], v[162:163], v[144:145]
	v_pk_fma_f32 v[146:147], v[64:65], v[162:163], v[146:147]
	v_pk_fma_f32 v[148:149], v[62:63], v[162:163], v[148:149]
	v_pk_fma_f32 v[152:153], v[60:61], v[162:163], v[152:153]
	v_pk_fma_f32 v[154:155], v[52:53], v[162:163], v[154:155]
	v_pk_fma_f32 v[156:157], v[50:51], v[162:163], v[156:157]
	v_pk_fma_f32 v[158:159], v[58:59], v[162:163], v[158:159]
	v_pk_fma_f32 v[160:161], v[56:57], v[162:163], v[160:161]
	v_pk_fma_f32 v[162:163], v[54:55], v[162:163], v[112:113]
	v_cndmask_b32_e32 v135, 0, v0, vcc
	s_waitcnt vmcnt(33)
	v_lshlrev_b32_e32 v0, 16, v136
	v_pk_fma_f32 v[142:143], v[70:71], v[164:165], v[142:143]
	v_pk_fma_f32 v[144:145], v[68:69], v[164:165], v[144:145]
	v_pk_fma_f32 v[146:147], v[66:67], v[164:165], v[146:147]
	v_pk_fma_f32 v[148:149], v[64:65], v[164:165], v[148:149]
	v_pk_fma_f32 v[152:153], v[62:63], v[164:165], v[152:153]
	v_pk_fma_f32 v[154:155], v[60:61], v[164:165], v[154:155]
	v_pk_fma_f32 v[156:157], v[52:53], v[164:165], v[156:157]
	v_pk_fma_f32 v[158:159], v[50:51], v[164:165], v[158:159]
	v_pk_fma_f32 v[160:161], v[58:59], v[164:165], v[160:161]
	v_pk_fma_f32 v[162:163], v[56:57], v[164:165], v[162:163]
	v_pk_fma_f32 v[164:165], v[54:55], v[164:165], v[112:113]
	v_cndmask_b32_e64 v166, 0, v0, s[74:75]
	v_and_b32_e32 v0, 0xffff0000, v136
	v_pk_fma_f32 v[142:143], v[72:73], v[134:135], v[142:143]
	v_pk_fma_f32 v[144:145], v[70:71], v[134:135], v[144:145]
	v_pk_fma_f32 v[146:147], v[68:69], v[134:135], v[146:147]
	v_pk_fma_f32 v[148:149], v[66:67], v[134:135], v[148:149]
	v_pk_fma_f32 v[152:153], v[64:65], v[134:135], v[152:153]
	v_pk_fma_f32 v[154:155], v[62:63], v[134:135], v[154:155]
	v_pk_fma_f32 v[156:157], v[60:61], v[134:135], v[156:157]
	v_pk_fma_f32 v[158:159], v[52:53], v[134:135], v[158:159]
	v_pk_fma_f32 v[160:161], v[50:51], v[134:135], v[160:161]
	v_pk_fma_f32 v[162:163], v[58:59], v[134:135], v[162:163]
	v_pk_fma_f32 v[164:165], v[56:57], v[134:135], v[164:165]
	v_pk_fma_f32 v[134:135], v[54:55], v[134:135], v[112:113]
	v_cndmask_b32_e64 v167, 0, v0, s[74:75]
	s_waitcnt vmcnt(32)
	v_lshlrev_b32_e32 v0, 16, v121
	v_pk_fma_f32 v[136:137], v[74:75], v[166:167], v[142:143]
	v_pk_fma_f32 v[142:143], v[72:73], v[166:167], v[144:145]
	v_pk_fma_f32 v[144:145], v[70:71], v[166:167], v[146:147]
	v_pk_fma_f32 v[146:147], v[68:69], v[166:167], v[148:149]
	v_pk_fma_f32 v[148:149], v[66:67], v[166:167], v[152:153]
	v_pk_fma_f32 v[152:153], v[64:65], v[166:167], v[154:155]
	v_pk_fma_f32 v[154:155], v[62:63], v[166:167], v[156:157]
	v_pk_fma_f32 v[156:157], v[60:61], v[166:167], v[158:159]
	v_pk_fma_f32 v[158:159], v[52:53], v[166:167], v[160:161]
	v_pk_fma_f32 v[160:161], v[50:51], v[166:167], v[162:163]
	v_pk_fma_f32 v[162:163], v[58:59], v[166:167], v[164:165]
	v_pk_fma_f32 v[134:135], v[56:57], v[166:167], v[134:135]
	v_pk_fma_f32 v[164:165], v[54:55], v[166:167], v[112:113]
	v_cndmask_b32_e32 v166, 0, v0, vcc
	v_and_b32_e32 v0, 0xffff0000, v121
	s_cmp_ge_i32 s2, s89
	v_cndmask_b32_e32 v167, 0, v0, vcc
	s_waitcnt vmcnt(31)
	v_lshlrev_b32_e32 v0, 16, v49
	s_cselect_b64 s[0:1], -1, 0
	s_cmp_lt_i32 s2, s88
	v_cndmask_b32_e32 v168, 0, v0, vcc
	v_and_b32_e32 v0, 0xffff0000, v49
	s_cselect_b64 s[6:7], -1, 0
	v_cndmask_b32_e32 v169, 0, v0, vcc
	s_waitcnt vmcnt(30)
	v_lshlrev_b32_e32 v0, 16, v47
	s_and_b64 vcc, s[0:1], s[6:7]
	v_cndmask_b32_e32 v170, 0, v0, vcc
	v_and_b32_e32 v0, 0xffff0000, v47
	v_pk_fma_f32 v[136:137], v[76:77], v[166:167], v[136:137]
	v_pk_fma_f32 v[142:143], v[74:75], v[166:167], v[142:143]
	v_pk_fma_f32 v[144:145], v[72:73], v[166:167], v[144:145]
	v_pk_fma_f32 v[146:147], v[70:71], v[166:167], v[146:147]
	v_pk_fma_f32 v[148:149], v[68:69], v[166:167], v[148:149]
	v_pk_fma_f32 v[152:153], v[66:67], v[166:167], v[152:153]
	v_pk_fma_f32 v[154:155], v[64:65], v[166:167], v[154:155]
	v_pk_fma_f32 v[156:157], v[62:63], v[166:167], v[156:157]
	v_pk_fma_f32 v[158:159], v[60:61], v[166:167], v[158:159]
	v_pk_fma_f32 v[160:161], v[52:53], v[166:167], v[160:161]
	v_pk_fma_f32 v[162:163], v[50:51], v[166:167], v[162:163]
	v_pk_fma_f32 v[134:135], v[58:59], v[166:167], v[134:135]
	v_pk_fma_f32 v[164:165], v[56:57], v[166:167], v[164:165]
	v_pk_fma_f32 v[166:167], v[54:55], v[166:167], v[112:113]
	v_cndmask_b32_e32 v171, 0, v0, vcc
	s_waitcnt vmcnt(29)
	v_lshlrev_b32_e32 v0, 16, v48
	v_pk_fma_f32 v[136:137], v[78:79], v[168:169], v[136:137]
	v_pk_fma_f32 v[142:143], v[76:77], v[168:169], v[142:143]
	v_pk_fma_f32 v[144:145], v[74:75], v[168:169], v[144:145]
	v_pk_fma_f32 v[146:147], v[72:73], v[168:169], v[146:147]
	v_pk_fma_f32 v[148:149], v[70:71], v[168:169], v[148:149]
	v_pk_fma_f32 v[152:153], v[68:69], v[168:169], v[152:153]
	v_pk_fma_f32 v[154:155], v[66:67], v[168:169], v[154:155]
	v_pk_fma_f32 v[156:157], v[64:65], v[168:169], v[156:157]
	v_pk_fma_f32 v[158:159], v[62:63], v[168:169], v[158:159]
	v_pk_fma_f32 v[160:161], v[60:61], v[168:169], v[160:161]
	v_pk_fma_f32 v[162:163], v[52:53], v[168:169], v[162:163]
	v_pk_fma_f32 v[134:135], v[50:51], v[168:169], v[134:135]
	v_pk_fma_f32 v[164:165], v[58:59], v[168:169], v[164:165]
	v_pk_fma_f32 v[166:167], v[56:57], v[168:169], v[166:167]
	v_pk_fma_f32 v[168:169], v[54:55], v[168:169], v[112:113]
	v_cndmask_b32_e64 v172, 0, v0, s[64:65]
	v_and_b32_e32 v0, 0xffff0000, v48
	v_pk_fma_f32 v[136:137], v[80:81], v[170:171], v[136:137]
	v_pk_fma_f32 v[142:143], v[78:79], v[170:171], v[142:143]
	v_pk_fma_f32 v[144:145], v[76:77], v[170:171], v[144:145]
	v_pk_fma_f32 v[146:147], v[74:75], v[170:171], v[146:147]
	v_pk_fma_f32 v[148:149], v[72:73], v[170:171], v[148:149]
	v_pk_fma_f32 v[152:153], v[70:71], v[170:171], v[152:153]
	v_pk_fma_f32 v[154:155], v[68:69], v[170:171], v[154:155]
	v_pk_fma_f32 v[156:157], v[66:67], v[170:171], v[156:157]
	v_pk_fma_f32 v[158:159], v[64:65], v[170:171], v[158:159]
	v_pk_fma_f32 v[160:161], v[62:63], v[170:171], v[160:161]
	v_pk_fma_f32 v[162:163], v[60:61], v[170:171], v[162:163]
	v_pk_fma_f32 v[134:135], v[52:53], v[170:171], v[134:135]
	v_pk_fma_f32 v[164:165], v[50:51], v[170:171], v[164:165]
	v_pk_fma_f32 v[166:167], v[58:59], v[170:171], v[166:167]
	v_pk_fma_f32 v[168:169], v[56:57], v[170:171], v[168:169]
	v_pk_fma_f32 v[170:171], v[54:55], v[170:171], v[112:113]
	v_cndmask_b32_e64 v173, 0, v0, s[64:65]
	s_waitcnt vmcnt(28)
	v_lshlrev_b32_e32 v0, 16, v46
	v_pk_fma_f32 v[48:49], v[82:83], v[172:173], v[136:137]
	v_pk_fma_f32 v[136:137], v[80:81], v[172:173], v[142:143]
	v_pk_fma_f32 v[142:143], v[78:79], v[172:173], v[144:145]
	v_pk_fma_f32 v[144:145], v[76:77], v[172:173], v[146:147]
	v_pk_fma_f32 v[146:147], v[74:75], v[172:173], v[148:149]
	v_pk_fma_f32 v[148:149], v[72:73], v[172:173], v[152:153]
	v_pk_fma_f32 v[152:153], v[70:71], v[172:173], v[154:155]
	v_pk_fma_f32 v[154:155], v[68:69], v[172:173], v[156:157]
	v_pk_fma_f32 v[156:157], v[66:67], v[172:173], v[158:159]
	v_pk_fma_f32 v[158:159], v[64:65], v[172:173], v[160:161]
	v_pk_fma_f32 v[160:161], v[62:63], v[172:173], v[162:163]
	v_pk_fma_f32 v[162:163], v[52:53], v[172:173], v[164:165]
	v_pk_fma_f32 v[164:165], v[50:51], v[172:173], v[166:167]
	v_pk_fma_f32 v[166:167], v[58:59], v[172:173], v[168:169]
	v_pk_fma_f32 v[168:169], v[56:57], v[172:173], v[170:171]
	v_cndmask_b32_e64 v170, 0, v0, s[62:63]
	v_and_b32_e32 v0, 0xffff0000, v46
	v_cndmask_b32_e64 v171, 0, v0, s[62:63]
	s_waitcnt vmcnt(27)
	v_lshlrev_b32_e32 v0, 16, v44
	v_pk_fma_f32 v[134:135], v[60:61], v[172:173], v[134:135]
	v_pk_fma_f32 v[46:47], v[84:85], v[170:171], v[48:49]
	v_pk_fma_f32 v[48:49], v[82:83], v[170:171], v[136:137]
	v_pk_fma_f32 v[136:137], v[80:81], v[170:171], v[142:143]
	v_pk_fma_f32 v[142:143], v[78:79], v[170:171], v[144:145]
	v_pk_fma_f32 v[144:145], v[76:77], v[170:171], v[146:147]
	v_pk_fma_f32 v[146:147], v[74:75], v[170:171], v[148:149]
	v_pk_fma_f32 v[148:149], v[72:73], v[170:171], v[152:153]
	v_pk_fma_f32 v[152:153], v[70:71], v[170:171], v[154:155]
	v_pk_fma_f32 v[154:155], v[68:69], v[170:171], v[156:157]
	v_pk_fma_f32 v[156:157], v[66:67], v[170:171], v[158:159]
	v_pk_fma_f32 v[158:159], v[64:65], v[170:171], v[160:161]
	v_pk_fma_f32 v[160:161], v[60:61], v[170:171], v[162:163]
	v_pk_fma_f32 v[162:163], v[52:53], v[170:171], v[164:165]
	v_pk_fma_f32 v[164:165], v[50:51], v[170:171], v[166:167]
	v_pk_fma_f32 v[166:167], v[58:59], v[170:171], v[168:169]
	v_cndmask_b32_e64 v168, 0, v0, s[60:61]
	v_and_b32_e32 v0, 0xffff0000, v44
	v_pk_fma_f32 v[134:135], v[62:63], v[170:171], v[134:135]
	v_cndmask_b32_e64 v169, 0, v0, s[60:61]
	s_waitcnt vmcnt(26)
	v_lshlrev_b32_e32 v0, 16, v42
	v_pk_fma_f32 v[46:47], v[86:87], v[168:169], v[46:47]
	v_pk_fma_f32 v[48:49], v[84:85], v[168:169], v[48:49]
	v_pk_fma_f32 v[136:137], v[82:83], v[168:169], v[136:137]
	v_pk_fma_f32 v[142:143], v[80:81], v[168:169], v[142:143]
	v_pk_fma_f32 v[144:145], v[78:79], v[168:169], v[144:145]
	v_pk_fma_f32 v[146:147], v[76:77], v[168:169], v[146:147]
	v_pk_fma_f32 v[148:149], v[74:75], v[168:169], v[148:149]
	v_pk_fma_f32 v[152:153], v[72:73], v[168:169], v[152:153]
	v_pk_fma_f32 v[154:155], v[70:71], v[168:169], v[154:155]
	v_pk_fma_f32 v[156:157], v[68:69], v[168:169], v[156:157]
	v_pk_fma_f32 v[158:159], v[66:67], v[168:169], v[158:159]
	v_pk_fma_f32 v[134:135], v[64:65], v[168:169], v[134:135]
	v_pk_fma_f32 v[160:161], v[62:63], v[168:169], v[160:161]
	v_pk_fma_f32 v[162:163], v[60:61], v[168:169], v[162:163]
	v_pk_fma_f32 v[164:165], v[52:53], v[168:169], v[164:165]
	v_pk_fma_f32 v[166:167], v[50:51], v[168:169], v[166:167]
	v_cndmask_b32_e64 v168, 0, v0, s[56:57]
	v_and_b32_e32 v0, 0xffff0000, v42
	v_cndmask_b32_e64 v169, 0, v0, s[56:57]
	s_waitcnt vmcnt(25)
	v_lshlrev_b32_e32 v0, 16, v39
	v_cndmask_b32_e64 v38, 0, v0, s[52:53]
	v_and_b32_e32 v0, 0xffff0000, v39
	v_pk_fma_f32 v[42:43], v[88:89], v[168:169], v[46:47]
	v_pk_fma_f32 v[46:47], v[86:87], v[168:169], v[48:49]
	v_pk_fma_f32 v[48:49], v[84:85], v[168:169], v[136:137]
	v_pk_fma_f32 v[136:137], v[82:83], v[168:169], v[142:143]
	v_pk_fma_f32 v[142:143], v[80:81], v[168:169], v[144:145]
	v_pk_fma_f32 v[144:145], v[78:79], v[168:169], v[146:147]
	v_pk_fma_f32 v[146:147], v[76:77], v[168:169], v[148:149]
	v_pk_fma_f32 v[148:149], v[74:75], v[168:169], v[152:153]
	v_pk_fma_f32 v[152:153], v[72:73], v[168:169], v[154:155]
	v_pk_fma_f32 v[154:155], v[70:71], v[168:169], v[156:157]
	v_pk_fma_f32 v[156:157], v[68:69], v[168:169], v[158:159]
	v_pk_fma_f32 v[134:135], v[66:67], v[168:169], v[134:135]
	v_pk_fma_f32 v[158:159], v[64:65], v[168:169], v[160:161]
	v_pk_fma_f32 v[160:161], v[62:63], v[168:169], v[162:163]
	v_pk_fma_f32 v[162:163], v[60:61], v[168:169], v[164:165]
	v_pk_fma_f32 v[164:165], v[52:53], v[168:169], v[166:167]
	v_cndmask_b32_e64 v39, 0, v0, s[52:53]
	s_waitcnt vmcnt(24)
	v_lshlrev_b32_e32 v0, 16, v36
	v_pk_fma_f32 v[42:43], v[90:91], v[38:39], v[42:43]
	v_pk_fma_f32 v[46:47], v[88:89], v[38:39], v[46:47]
	v_pk_fma_f32 v[48:49], v[86:87], v[38:39], v[48:49]
	v_pk_fma_f32 v[136:137], v[84:85], v[38:39], v[136:137]
	v_pk_fma_f32 v[142:143], v[82:83], v[38:39], v[142:143]
	v_pk_fma_f32 v[144:145], v[80:81], v[38:39], v[144:145]
	v_pk_fma_f32 v[146:147], v[78:79], v[38:39], v[146:147]
	v_pk_fma_f32 v[148:149], v[76:77], v[38:39], v[148:149]
	v_pk_fma_f32 v[152:153], v[74:75], v[38:39], v[152:153]
	v_pk_fma_f32 v[154:155], v[72:73], v[38:39], v[154:155]
	v_pk_fma_f32 v[156:157], v[70:71], v[38:39], v[156:157]
	v_pk_fma_f32 v[134:135], v[68:69], v[38:39], v[134:135]
	v_pk_fma_f32 v[158:159], v[66:67], v[38:39], v[158:159]
	v_pk_fma_f32 v[160:161], v[64:65], v[38:39], v[160:161]
	v_pk_fma_f32 v[162:163], v[62:63], v[38:39], v[162:163]
	v_pk_fma_f32 v[38:39], v[60:61], v[38:39], v[164:165]
	v_cndmask_b32_e64 v164, 0, v0, s[44:45]
	v_and_b32_e32 v0, 0xffff0000, v36
	v_cndmask_b32_e64 v165, 0, v0, s[44:45]
	s_waitcnt vmcnt(23)
	v_lshlrev_b32_e32 v0, 16, v33
	v_cndmask_b32_e64 v32, 0, v0, s[38:39]
	v_and_b32_e32 v0, 0xffff0000, v33
	v_pk_fma_f32 v[42:43], v[92:93], v[164:165], v[42:43]
	v_pk_fma_f32 v[46:47], v[90:91], v[164:165], v[46:47]
	v_pk_fma_f32 v[48:49], v[88:89], v[164:165], v[48:49]
	v_pk_fma_f32 v[136:137], v[86:87], v[164:165], v[136:137]
	v_pk_fma_f32 v[142:143], v[84:85], v[164:165], v[142:143]
	v_pk_fma_f32 v[144:145], v[82:83], v[164:165], v[144:145]
	v_pk_fma_f32 v[146:147], v[80:81], v[164:165], v[146:147]
	v_pk_fma_f32 v[148:149], v[78:79], v[164:165], v[148:149]
	v_pk_fma_f32 v[152:153], v[76:77], v[164:165], v[152:153]
	v_pk_fma_f32 v[154:155], v[74:75], v[164:165], v[154:155]
	v_pk_fma_f32 v[156:157], v[72:73], v[164:165], v[156:157]
	v_pk_fma_f32 v[134:135], v[70:71], v[164:165], v[134:135]
	v_pk_fma_f32 v[158:159], v[68:69], v[164:165], v[158:159]
	v_pk_fma_f32 v[160:161], v[66:67], v[164:165], v[160:161]
	v_pk_fma_f32 v[162:163], v[64:65], v[164:165], v[162:163]
	v_pk_fma_f32 v[38:39], v[62:63], v[164:165], v[38:39]
	v_cndmask_b32_e64 v33, 0, v0, s[38:39]
	s_waitcnt vmcnt(22)
	v_lshlrev_b32_e32 v0, 16, v40
	v_pk_fma_f32 v[42:43], v[94:95], v[32:33], v[42:43]
	v_pk_fma_f32 v[46:47], v[92:93], v[32:33], v[46:47]
	v_pk_fma_f32 v[48:49], v[90:91], v[32:33], v[48:49]
	v_pk_fma_f32 v[136:137], v[88:89], v[32:33], v[136:137]
	v_pk_fma_f32 v[142:143], v[86:87], v[32:33], v[142:143]
	v_pk_fma_f32 v[144:145], v[84:85], v[32:33], v[144:145]
	v_pk_fma_f32 v[146:147], v[82:83], v[32:33], v[146:147]
	v_pk_fma_f32 v[148:149], v[80:81], v[32:33], v[148:149]
	v_pk_fma_f32 v[152:153], v[78:79], v[32:33], v[152:153]
	v_pk_fma_f32 v[154:155], v[76:77], v[32:33], v[154:155]
	v_pk_fma_f32 v[156:157], v[74:75], v[32:33], v[156:157]
	v_pk_fma_f32 v[134:135], v[72:73], v[32:33], v[134:135]
	v_pk_fma_f32 v[158:159], v[70:71], v[32:33], v[158:159]
	v_pk_fma_f32 v[160:161], v[68:69], v[32:33], v[160:161]
	v_pk_fma_f32 v[162:163], v[66:67], v[32:33], v[162:163]
	v_pk_fma_f32 v[32:33], v[64:65], v[32:33], v[38:39]
	v_cndmask_b32_e64 v38, 0, v0, s[24:25]
	v_and_b32_e32 v0, 0xffff0000, v40
	v_cndmask_b32_e64 v39, 0, v0, s[24:25]
	s_waitcnt vmcnt(21)
	v_lshlrev_b32_e32 v0, 16, v41
	v_pk_fma_f32 v[42:43], v[96:97], v[38:39], v[42:43]
	v_pk_fma_f32 v[46:47], v[94:95], v[38:39], v[46:47]
	v_pk_fma_f32 v[48:49], v[92:93], v[38:39], v[48:49]
	v_pk_fma_f32 v[136:137], v[90:91], v[38:39], v[136:137]
	v_pk_fma_f32 v[142:143], v[88:89], v[38:39], v[142:143]
	v_pk_fma_f32 v[144:145], v[86:87], v[38:39], v[144:145]
	v_pk_fma_f32 v[146:147], v[84:85], v[38:39], v[146:147]
	v_pk_fma_f32 v[148:149], v[82:83], v[38:39], v[148:149]
	v_pk_fma_f32 v[152:153], v[80:81], v[38:39], v[152:153]
	v_pk_fma_f32 v[154:155], v[78:79], v[38:39], v[154:155]
	v_pk_fma_f32 v[156:157], v[76:77], v[38:39], v[156:157]
	v_pk_fma_f32 v[134:135], v[74:75], v[38:39], v[134:135]
	v_pk_fma_f32 v[158:159], v[72:73], v[38:39], v[158:159]
	v_pk_fma_f32 v[160:161], v[70:71], v[38:39], v[160:161]
	v_pk_fma_f32 v[162:163], v[68:69], v[38:39], v[162:163]
	v_pk_fma_f32 v[32:33], v[66:67], v[38:39], v[32:33]
	v_cndmask_b32_e64 v38, 0, v0, s[54:55]
	v_and_b32_e32 v0, 0xffff0000, v41
	v_cndmask_b32_e64 v39, 0, v0, s[54:55]
	s_waitcnt vmcnt(20)
	v_lshlrev_b32_e32 v0, 16, v37
	v_cndmask_b32_e64 v36, 0, v0, s[48:49]
	v_and_b32_e32 v0, 0xffff0000, v37
	v_pk_fma_f32 v[40:41], v[98:99], v[38:39], v[42:43]
	v_pk_fma_f32 v[42:43], v[96:97], v[38:39], v[46:47]
	v_pk_fma_f32 v[46:47], v[94:95], v[38:39], v[48:49]
	v_pk_fma_f32 v[48:49], v[92:93], v[38:39], v[136:137]
	v_pk_fma_f32 v[136:137], v[90:91], v[38:39], v[142:143]
	v_pk_fma_f32 v[142:143], v[88:89], v[38:39], v[144:145]
	v_pk_fma_f32 v[144:145], v[86:87], v[38:39], v[146:147]
	v_pk_fma_f32 v[146:147], v[84:85], v[38:39], v[148:149]
	v_pk_fma_f32 v[148:149], v[82:83], v[38:39], v[152:153]
	v_pk_fma_f32 v[152:153], v[80:81], v[38:39], v[154:155]
	v_pk_fma_f32 v[154:155], v[78:79], v[38:39], v[156:157]
	v_pk_fma_f32 v[134:135], v[76:77], v[38:39], v[134:135]
	v_pk_fma_f32 v[156:157], v[74:75], v[38:39], v[158:159]
	v_pk_fma_f32 v[158:159], v[72:73], v[38:39], v[160:161]
	v_pk_fma_f32 v[160:161], v[70:71], v[38:39], v[162:163]
	v_pk_fma_f32 v[32:33], v[68:69], v[38:39], v[32:33]
	v_cndmask_b32_e64 v37, 0, v0, s[48:49]
	s_waitcnt vmcnt(19)
	v_lshlrev_b32_e32 v0, 16, v35
	v_pk_fma_f32 v[38:39], v[100:101], v[36:37], v[40:41]
	v_pk_fma_f32 v[40:41], v[98:99], v[36:37], v[42:43]
	v_pk_fma_f32 v[42:43], v[96:97], v[36:37], v[46:47]
	v_pk_fma_f32 v[46:47], v[94:95], v[36:37], v[48:49]
	v_pk_fma_f32 v[48:49], v[92:93], v[36:37], v[136:137]
	v_pk_fma_f32 v[136:137], v[90:91], v[36:37], v[142:143]
	v_pk_fma_f32 v[142:143], v[88:89], v[36:37], v[144:145]
	v_pk_fma_f32 v[144:145], v[86:87], v[36:37], v[146:147]
	v_pk_fma_f32 v[146:147], v[84:85], v[36:37], v[148:149]
	v_pk_fma_f32 v[148:149], v[82:83], v[36:37], v[152:153]
	v_pk_fma_f32 v[152:153], v[80:81], v[36:37], v[154:155]
	v_pk_fma_f32 v[134:135], v[78:79], v[36:37], v[134:135]
	v_pk_fma_f32 v[154:155], v[76:77], v[36:37], v[156:157]
	v_pk_fma_f32 v[156:157], v[74:75], v[36:37], v[158:159]
	v_pk_fma_f32 v[158:159], v[72:73], v[36:37], v[160:161]
	v_pk_fma_f32 v[32:33], v[70:71], v[36:37], v[32:33]
	v_cndmask_b32_e64 v36, 0, v0, s[42:43]
	v_and_b32_e32 v0, 0xffff0000, v35
	v_cndmask_b32_e64 v37, 0, v0, s[42:43]
	s_waitcnt vmcnt(18)
	v_lshlrev_b32_e32 v0, 16, v30
	v_pk_fma_f32 v[38:39], v[102:103], v[36:37], v[38:39]
	v_pk_fma_f32 v[40:41], v[100:101], v[36:37], v[40:41]
	v_pk_fma_f32 v[42:43], v[98:99], v[36:37], v[42:43]
	v_pk_fma_f32 v[46:47], v[96:97], v[36:37], v[46:47]
	v_pk_fma_f32 v[48:49], v[94:95], v[36:37], v[48:49]
	v_pk_fma_f32 v[136:137], v[92:93], v[36:37], v[136:137]
	v_pk_fma_f32 v[142:143], v[90:91], v[36:37], v[142:143]
	v_pk_fma_f32 v[144:145], v[88:89], v[36:37], v[144:145]
	v_pk_fma_f32 v[146:147], v[86:87], v[36:37], v[146:147]
	v_pk_fma_f32 v[148:149], v[84:85], v[36:37], v[148:149]
	v_pk_fma_f32 v[152:153], v[82:83], v[36:37], v[152:153]
	v_pk_fma_f32 v[134:135], v[80:81], v[36:37], v[134:135]
	v_pk_fma_f32 v[154:155], v[78:79], v[36:37], v[154:155]
	v_pk_fma_f32 v[156:157], v[76:77], v[36:37], v[156:157]
	v_pk_fma_f32 v[158:159], v[74:75], v[36:37], v[158:159]
	v_pk_fma_f32 v[32:33], v[72:73], v[36:37], v[32:33]
	v_cndmask_b32_e64 v36, 0, v0, s[34:35]
	v_and_b32_e32 v0, 0xffff0000, v30
	v_cndmask_b32_e64 v37, 0, v0, s[34:35]
	s_waitcnt vmcnt(17)
	v_lshlrev_b32_e32 v0, 16, v22
	v_pk_fma_f32 v[38:39], v[104:105], v[36:37], v[38:39]
	v_pk_fma_f32 v[40:41], v[102:103], v[36:37], v[40:41]
	v_pk_fma_f32 v[42:43], v[100:101], v[36:37], v[42:43]
	v_pk_fma_f32 v[46:47], v[98:99], v[36:37], v[46:47]
	v_pk_fma_f32 v[48:49], v[96:97], v[36:37], v[48:49]
	v_pk_fma_f32 v[136:137], v[94:95], v[36:37], v[136:137]
	v_pk_fma_f32 v[142:143], v[92:93], v[36:37], v[142:143]
	v_pk_fma_f32 v[144:145], v[90:91], v[36:37], v[144:145]
	v_pk_fma_f32 v[146:147], v[88:89], v[36:37], v[146:147]
	v_pk_fma_f32 v[148:149], v[86:87], v[36:37], v[148:149]
	v_pk_fma_f32 v[152:153], v[84:85], v[36:37], v[152:153]
	v_pk_fma_f32 v[134:135], v[82:83], v[36:37], v[134:135]
	v_pk_fma_f32 v[154:155], v[80:81], v[36:37], v[154:155]
	v_pk_fma_f32 v[156:157], v[78:79], v[36:37], v[156:157]
	v_pk_fma_f32 v[158:159], v[76:77], v[36:37], v[158:159]
	v_pk_fma_f32 v[32:33], v[74:75], v[36:37], v[32:33]
	v_cndmask_b32_e64 v36, 0, v0, s[14:15]
	v_and_b32_e32 v0, 0xffff0000, v22
	v_cndmask_b32_e64 v37, 0, v0, s[14:15]
	s_waitcnt vmcnt(16)
	v_lshlrev_b32_e32 v0, 16, v20
	v_pk_fma_f32 v[38:39], v[106:107], v[36:37], v[38:39]
	v_pk_fma_f32 v[40:41], v[104:105], v[36:37], v[40:41]
	v_pk_fma_f32 v[42:43], v[102:103], v[36:37], v[42:43]
	v_pk_fma_f32 v[46:47], v[100:101], v[36:37], v[46:47]
	v_pk_fma_f32 v[48:49], v[98:99], v[36:37], v[48:49]
	v_pk_fma_f32 v[136:137], v[96:97], v[36:37], v[136:137]
	v_pk_fma_f32 v[142:143], v[94:95], v[36:37], v[142:143]
	v_pk_fma_f32 v[144:145], v[92:93], v[36:37], v[144:145]
	v_pk_fma_f32 v[146:147], v[90:91], v[36:37], v[146:147]
	v_pk_fma_f32 v[148:149], v[88:89], v[36:37], v[148:149]
	v_pk_fma_f32 v[152:153], v[86:87], v[36:37], v[152:153]
	v_pk_fma_f32 v[134:135], v[84:85], v[36:37], v[134:135]
	v_pk_fma_f32 v[154:155], v[82:83], v[36:37], v[154:155]
	v_pk_fma_f32 v[156:157], v[80:81], v[36:37], v[156:157]
	v_pk_fma_f32 v[158:159], v[78:79], v[36:37], v[158:159]
	v_pk_fma_f32 v[32:33], v[76:77], v[36:37], v[32:33]
	v_cndmask_b32_e64 v36, 0, v0, s[10:11]
	v_and_b32_e32 v0, 0xffff0000, v20
	v_cndmask_b32_e64 v37, 0, v0, s[10:11]
	s_waitcnt vmcnt(15)
	v_lshlrev_b32_e32 v0, 16, v19
	v_cndmask_b32_e64 v18, 0, v0, s[8:9]
	v_and_b32_e32 v0, 0xffff0000, v19
	v_pk_fma_f32 v[20:21], v[108:109], v[36:37], v[38:39]
	v_pk_fma_f32 v[38:39], v[106:107], v[36:37], v[40:41]
	v_pk_fma_f32 v[40:41], v[104:105], v[36:37], v[42:43]
	v_pk_fma_f32 v[42:43], v[102:103], v[36:37], v[46:47]
	v_pk_fma_f32 v[46:47], v[100:101], v[36:37], v[48:49]
	v_pk_fma_f32 v[48:49], v[98:99], v[36:37], v[136:137]
	v_pk_fma_f32 v[136:137], v[96:97], v[36:37], v[142:143]
	v_pk_fma_f32 v[142:143], v[94:95], v[36:37], v[144:145]
	v_pk_fma_f32 v[144:145], v[92:93], v[36:37], v[146:147]
	v_pk_fma_f32 v[146:147], v[90:91], v[36:37], v[148:149]
	v_pk_fma_f32 v[148:149], v[88:89], v[36:37], v[152:153]
	v_pk_fma_f32 v[134:135], v[86:87], v[36:37], v[134:135]
	v_pk_fma_f32 v[152:153], v[84:85], v[36:37], v[154:155]
	v_pk_fma_f32 v[154:155], v[82:83], v[36:37], v[156:157]
	v_pk_fma_f32 v[156:157], v[80:81], v[36:37], v[158:159]
	v_pk_fma_f32 v[32:33], v[78:79], v[36:37], v[32:33]
	v_cndmask_b32_e64 v19, 0, v0, s[8:9]
	s_waitcnt vmcnt(14)
	v_lshlrev_b32_e32 v0, 16, v27
	v_pk_fma_f32 v[20:21], v[110:111], v[18:19], v[20:21]
	v_pk_fma_f32 v[36:37], v[108:109], v[18:19], v[38:39]
	v_pk_fma_f32 v[38:39], v[106:107], v[18:19], v[40:41]
	v_pk_fma_f32 v[40:41], v[104:105], v[18:19], v[42:43]
	v_pk_fma_f32 v[42:43], v[102:103], v[18:19], v[46:47]
	v_pk_fma_f32 v[46:47], v[100:101], v[18:19], v[48:49]
	v_pk_fma_f32 v[48:49], v[98:99], v[18:19], v[136:137]
	v_pk_fma_f32 v[136:137], v[96:97], v[18:19], v[142:143]
	v_pk_fma_f32 v[142:143], v[94:95], v[18:19], v[144:145]
	v_pk_fma_f32 v[144:145], v[92:93], v[18:19], v[146:147]
	v_pk_fma_f32 v[146:147], v[90:91], v[18:19], v[148:149]
	v_pk_fma_f32 v[134:135], v[88:89], v[18:19], v[134:135]
	v_pk_fma_f32 v[148:149], v[86:87], v[18:19], v[152:153]
	v_pk_fma_f32 v[152:153], v[84:85], v[18:19], v[154:155]
	v_pk_fma_f32 v[154:155], v[82:83], v[18:19], v[156:157]
	v_pk_fma_f32 v[18:19], v[80:81], v[18:19], v[32:33]
	v_cndmask_b32_e64 v32, 0, v0, s[4:5]
	v_and_b32_e32 v0, 0xffff0000, v27
	v_cndmask_b32_e64 v33, 0, v0, s[4:5]
	s_waitcnt vmcnt(13)
	v_lshlrev_b32_e32 v0, 16, v31
	v_cndmask_b32_e64 v30, 0, v0, s[26:27]
	v_and_b32_e32 v0, 0xffff0000, v31
	v_pk_fma_f32 v[38:39], v[108:109], v[32:33], v[38:39]
	v_pk_fma_f32 v[40:41], v[106:107], v[32:33], v[40:41]
	v_pk_fma_f32 v[42:43], v[104:105], v[32:33], v[42:43]
	v_pk_fma_f32 v[46:47], v[102:103], v[32:33], v[46:47]
	v_pk_fma_f32 v[48:49], v[100:101], v[32:33], v[48:49]
	v_pk_fma_f32 v[136:137], v[98:99], v[32:33], v[136:137]
	v_pk_fma_f32 v[142:143], v[96:97], v[32:33], v[142:143]
	v_pk_fma_f32 v[144:145], v[94:95], v[32:33], v[144:145]
	v_pk_fma_f32 v[146:147], v[92:93], v[32:33], v[146:147]
	v_pk_fma_f32 v[134:135], v[90:91], v[32:33], v[134:135]
	v_pk_fma_f32 v[148:149], v[88:89], v[32:33], v[148:149]
	v_pk_fma_f32 v[152:153], v[86:87], v[32:33], v[152:153]
	v_pk_fma_f32 v[154:155], v[84:85], v[32:33], v[154:155]
	v_pk_fma_f32 v[18:19], v[82:83], v[32:33], v[18:19]
	v_cndmask_b32_e64 v31, 0, v0, s[26:27]
	s_waitcnt vmcnt(12)
	v_lshlrev_b32_e32 v0, 16, v25
	v_pk_fma_f32 v[36:37], v[110:111], v[32:33], v[36:37]
	v_pk_fma_f32 v[32:33], v[110:111], v[30:31], v[38:39]
	v_pk_fma_f32 v[38:39], v[108:109], v[30:31], v[40:41]
	v_pk_fma_f32 v[40:41], v[106:107], v[30:31], v[42:43]
	v_pk_fma_f32 v[42:43], v[104:105], v[30:31], v[46:47]
	v_pk_fma_f32 v[46:47], v[102:103], v[30:31], v[48:49]
	v_pk_fma_f32 v[48:49], v[100:101], v[30:31], v[136:137]
	v_pk_fma_f32 v[136:137], v[98:99], v[30:31], v[142:143]
	v_pk_fma_f32 v[142:143], v[96:97], v[30:31], v[144:145]
	v_pk_fma_f32 v[144:145], v[94:95], v[30:31], v[146:147]
	v_pk_fma_f32 v[134:135], v[92:93], v[30:31], v[134:135]
	v_pk_fma_f32 v[146:147], v[90:91], v[30:31], v[148:149]
	v_pk_fma_f32 v[148:149], v[88:89], v[30:31], v[152:153]
	v_pk_fma_f32 v[152:153], v[86:87], v[30:31], v[154:155]
	v_pk_fma_f32 v[18:19], v[84:85], v[30:31], v[18:19]
	v_cndmask_b32_e64 v30, 0, v0, s[20:21]
	v_and_b32_e32 v0, 0xffff0000, v25
	v_cndmask_b32_e64 v31, 0, v0, s[20:21]
	s_waitcnt vmcnt(11)
	v_lshlrev_b32_e32 v0, 16, v23
	v_cndmask_b32_e64 v22, 0, v0, s[16:17]
	v_and_b32_e32 v0, 0xffff0000, v23
	v_pk_fma_f32 v[40:41], v[108:109], v[30:31], v[40:41]
	v_pk_fma_f32 v[42:43], v[106:107], v[30:31], v[42:43]
	v_pk_fma_f32 v[46:47], v[104:105], v[30:31], v[46:47]
	v_pk_fma_f32 v[48:49], v[102:103], v[30:31], v[48:49]
	v_pk_fma_f32 v[136:137], v[100:101], v[30:31], v[136:137]
	v_pk_fma_f32 v[142:143], v[98:99], v[30:31], v[142:143]
	v_pk_fma_f32 v[144:145], v[96:97], v[30:31], v[144:145]
	v_pk_fma_f32 v[134:135], v[94:95], v[30:31], v[134:135]
	v_pk_fma_f32 v[146:147], v[92:93], v[30:31], v[146:147]
	v_pk_fma_f32 v[148:149], v[90:91], v[30:31], v[148:149]
	v_pk_fma_f32 v[152:153], v[88:89], v[30:31], v[152:153]
	v_pk_fma_f32 v[18:19], v[86:87], v[30:31], v[18:19]
	v_cndmask_b32_e64 v23, 0, v0, s[16:17]
	s_waitcnt vmcnt(10)
	v_lshlrev_b32_e32 v0, 16, v24
	v_pk_fma_f32 v[38:39], v[110:111], v[30:31], v[38:39]
	v_pk_fma_f32 v[30:31], v[110:111], v[22:23], v[40:41]
	v_pk_fma_f32 v[40:41], v[108:109], v[22:23], v[42:43]
	v_pk_fma_f32 v[42:43], v[106:107], v[22:23], v[46:47]
	v_pk_fma_f32 v[46:47], v[104:105], v[22:23], v[48:49]
	v_pk_fma_f32 v[48:49], v[102:103], v[22:23], v[136:137]
	v_pk_fma_f32 v[136:137], v[100:101], v[22:23], v[142:143]
	v_pk_fma_f32 v[142:143], v[98:99], v[22:23], v[144:145]
	v_pk_fma_f32 v[134:135], v[96:97], v[22:23], v[134:135]
	v_pk_fma_f32 v[144:145], v[94:95], v[22:23], v[146:147]
	v_pk_fma_f32 v[146:147], v[92:93], v[22:23], v[148:149]
	v_pk_fma_f32 v[148:149], v[90:91], v[22:23], v[152:153]
	v_pk_fma_f32 v[18:19], v[88:89], v[22:23], v[18:19]
	v_cndmask_b32_e64 v22, 0, v0, s[18:19]
	v_and_b32_e32 v0, 0xffff0000, v24
	v_cndmask_b32_e64 v23, 0, v0, s[18:19]
	s_waitcnt vmcnt(9)
	v_lshlrev_b32_e32 v0, 16, v26
	v_pk_fma_f32 v[24:25], v[110:111], v[22:23], v[40:41]
	v_pk_fma_f32 v[40:41], v[108:109], v[22:23], v[42:43]
	v_pk_fma_f32 v[42:43], v[106:107], v[22:23], v[46:47]
	v_pk_fma_f32 v[46:47], v[104:105], v[22:23], v[48:49]
	v_pk_fma_f32 v[48:49], v[102:103], v[22:23], v[136:137]
	v_pk_fma_f32 v[136:137], v[100:101], v[22:23], v[142:143]
	v_pk_fma_f32 v[134:135], v[98:99], v[22:23], v[134:135]
	v_pk_fma_f32 v[142:143], v[96:97], v[22:23], v[144:145]
	v_pk_fma_f32 v[144:145], v[94:95], v[22:23], v[146:147]
	v_pk_fma_f32 v[146:147], v[92:93], v[22:23], v[148:149]
	v_pk_fma_f32 v[18:19], v[90:91], v[22:23], v[18:19]
	v_cndmask_b32_e64 v22, 0, v0, s[22:23]
	v_and_b32_e32 v0, 0xffff0000, v26
	v_cndmask_b32_e64 v23, 0, v0, s[22:23]
	s_waitcnt vmcnt(8)
	v_lshlrev_b32_e32 v0, 16, v28
	v_pk_fma_f32 v[26:27], v[110:111], v[22:23], v[40:41]
	v_pk_fma_f32 v[40:41], v[108:109], v[22:23], v[42:43]
	v_pk_fma_f32 v[42:43], v[106:107], v[22:23], v[46:47]
	v_pk_fma_f32 v[46:47], v[104:105], v[22:23], v[48:49]
	v_pk_fma_f32 v[48:49], v[102:103], v[22:23], v[136:137]
	v_pk_fma_f32 v[134:135], v[100:101], v[22:23], v[134:135]
	v_pk_fma_f32 v[136:137], v[98:99], v[22:23], v[142:143]
	v_pk_fma_f32 v[142:143], v[96:97], v[22:23], v[144:145]
	v_pk_fma_f32 v[144:145], v[94:95], v[22:23], v[146:147]
	v_pk_fma_f32 v[18:19], v[92:93], v[22:23], v[18:19]
	v_cndmask_b32_e64 v22, 0, v0, s[28:29]
	v_and_b32_e32 v0, 0xffff0000, v28
	v_cndmask_b32_e64 v23, 0, v0, s[28:29]
	s_waitcnt vmcnt(7)
	v_lshlrev_b32_e32 v0, 16, v34
	v_pk_fma_f32 v[28:29], v[110:111], v[22:23], v[40:41]
	v_pk_fma_f32 v[40:41], v[108:109], v[22:23], v[42:43]
	v_pk_fma_f32 v[42:43], v[106:107], v[22:23], v[46:47]
	v_pk_fma_f32 v[46:47], v[104:105], v[22:23], v[48:49]
	v_pk_fma_f32 v[48:49], v[102:103], v[22:23], v[134:135]
	v_pk_fma_f32 v[134:135], v[100:101], v[22:23], v[136:137]
	v_pk_fma_f32 v[136:137], v[98:99], v[22:23], v[142:143]
	v_pk_fma_f32 v[142:143], v[96:97], v[22:23], v[144:145]
	v_pk_fma_f32 v[18:19], v[94:95], v[22:23], v[18:19]
	v_cndmask_b32_e64 v22, 0, v0, s[40:41]
	v_and_b32_e32 v0, 0xffff0000, v34
	v_cndmask_b32_e64 v23, 0, v0, s[40:41]
	s_waitcnt vmcnt(6)
	v_lshlrev_b32_e32 v0, 16, v45
	v_pk_fma_f32 v[34:35], v[110:111], v[22:23], v[40:41]
	v_pk_fma_f32 v[40:41], v[108:109], v[22:23], v[42:43]
	v_pk_fma_f32 v[42:43], v[106:107], v[22:23], v[46:47]
	v_pk_fma_f32 v[46:47], v[104:105], v[22:23], v[48:49]
	v_pk_fma_f32 v[48:49], v[102:103], v[22:23], v[134:135]
	v_pk_fma_f32 v[134:135], v[100:101], v[22:23], v[136:137]
	v_pk_fma_f32 v[136:137], v[98:99], v[22:23], v[142:143]
	v_pk_fma_f32 v[18:19], v[96:97], v[22:23], v[18:19]
	v_cndmask_b32_e64 v22, 0, v0, s[46:47]
	v_and_b32_e32 v0, 0xffff0000, v45
	v_cndmask_b32_e64 v23, 0, v0, s[46:47]
	s_waitcnt vmcnt(5)
	v_lshlrev_b32_e32 v0, 16, v118
	v_pk_fma_f32 v[40:41], v[110:111], v[22:23], v[40:41]
	v_pk_fma_f32 v[42:43], v[108:109], v[22:23], v[42:43]
	v_pk_fma_f32 v[44:45], v[106:107], v[22:23], v[46:47]
	v_pk_fma_f32 v[46:47], v[104:105], v[22:23], v[48:49]
	v_pk_fma_f32 v[48:49], v[102:103], v[22:23], v[134:135]
	v_pk_fma_f32 v[134:135], v[100:101], v[22:23], v[136:137]
	v_pk_fma_f32 v[18:19], v[98:99], v[22:23], v[18:19]
	v_cndmask_b32_e64 v22, 0, v0, s[66:67]
	v_and_b32_e32 v0, 0xffff0000, v118
	v_cndmask_b32_e64 v23, 0, v0, s[66:67]
	s_waitcnt vmcnt(4)
	v_lshlrev_b32_e32 v0, 16, v120
	v_pk_fma_f32 v[42:43], v[110:111], v[22:23], v[42:43]
	v_pk_fma_f32 v[44:45], v[108:109], v[22:23], v[44:45]
	v_pk_fma_f32 v[46:47], v[106:107], v[22:23], v[46:47]
	v_pk_fma_f32 v[48:49], v[104:105], v[22:23], v[48:49]
	v_pk_fma_f32 v[118:119], v[102:103], v[22:23], v[134:135]
	v_pk_fma_f32 v[18:19], v[100:101], v[22:23], v[18:19]
	v_cndmask_b32_e64 v22, 0, v0, s[68:69]
	v_and_b32_e32 v0, 0xffff0000, v120
	v_cndmask_b32_e64 v23, 0, v0, s[68:69]
	s_waitcnt vmcnt(3)
	v_lshlrev_b32_e32 v0, 16, v133
	v_pk_fma_f32 v[44:45], v[110:111], v[22:23], v[44:45]
	v_pk_fma_f32 v[46:47], v[108:109], v[22:23], v[46:47]
	v_pk_fma_f32 v[48:49], v[106:107], v[22:23], v[48:49]
	v_pk_fma_f32 v[118:119], v[104:105], v[22:23], v[118:119]
	v_pk_fma_f32 v[18:19], v[102:103], v[22:23], v[18:19]
	v_cndmask_b32_e64 v22, 0, v0, s[72:73]
	v_and_b32_e32 v0, 0xffff0000, v133
	v_cndmask_b32_e64 v23, 0, v0, s[72:73]
	s_waitcnt vmcnt(2)
	v_lshlrev_b32_e32 v0, 16, v139
	v_pk_fma_f32 v[46:47], v[110:111], v[22:23], v[46:47]
	v_pk_fma_f32 v[48:49], v[108:109], v[22:23], v[48:49]
	v_pk_fma_f32 v[118:119], v[106:107], v[22:23], v[118:119]
	v_pk_fma_f32 v[18:19], v[104:105], v[22:23], v[18:19]
	v_cndmask_b32_e64 v22, 0, v0, s[80:81]
	v_and_b32_e32 v0, 0xffff0000, v139
	v_cndmask_b32_e64 v23, 0, v0, s[80:81]
	s_waitcnt vmcnt(1)
	v_lshlrev_b32_e32 v0, 16, v140
	v_pk_fma_f32 v[48:49], v[110:111], v[22:23], v[48:49]
	v_pk_fma_f32 v[118:119], v[108:109], v[22:23], v[118:119]
	v_pk_fma_f32 v[18:19], v[106:107], v[22:23], v[18:19]
	v_cndmask_b32_e64 v22, 0, v0, s[82:83]
	v_and_b32_e32 v0, 0xffff0000, v140
	v_cndmask_b32_e64 v23, 0, v0, s[82:83]
	s_waitcnt vmcnt(0)
	v_lshlrev_b32_e32 v0, 16, v141
	v_pk_fma_f32 v[118:119], v[110:111], v[22:23], v[118:119]
	v_pk_fma_f32 v[18:19], v[108:109], v[22:23], v[18:19]
	v_cndmask_b32_e64 v22, 0, v0, s[84:85]
	v_and_b32_e32 v0, 0xffff0000, v141
	v_cndmask_b32_e64 v23, 0, v0, s[84:85]
	v_pk_fma_f32 v[18:19], v[110:111], v[22:23], v[18:19]
.Ldw_tail:
	ds_write2st64_b64 v122, v[20:21], v[36:37] offset1:8
	ds_write2st64_b64 v122, v[32:33], v[38:39] offset0:16 offset1:24
	ds_write2st64_b64 v122, v[30:31], v[24:25] offset0:32 offset1:40
	ds_write2st64_b64 v122, v[26:27], v[28:29] offset0:48 offset1:56
	ds_write2st64_b64 v122, v[34:35], v[40:41] offset0:64 offset1:72
	ds_write2st64_b64 v122, v[42:43], v[44:45] offset0:80 offset1:88
	ds_write2st64_b64 v122, v[46:47], v[48:49] offset0:96 offset1:104
	ds_write2st64_b64 v122, v[118:119], v[18:19] offset0:112 offset1:120
	s_waitcnt lgkmcnt(0)
	s_barrier
	ds_read_b128 v[46:49], v131
	ds_read_b128 v[42:45], v131 offset:1024
	ds_read_b128 v[38:41], v131 offset:2048
	ds_read_b128 v[34:37], v131 offset:3072
	ds_read_b128 v[30:33], v132
	ds_read_b128 v[26:29], v132 offset:1024
	s_waitcnt lgkmcnt(5)
	v_mov_b32_e32 v18, v47
	v_mov_b32_e32 v19, v48
	v_mov_b32_e32 v20, v46
	v_mov_b32_e32 v21, v49
	v_pk_add_f32 v[18:19], v[18:19], v[20:21]
	s_waitcnt lgkmcnt(4)
	v_mov_b32_e32 v20, v43
	v_mov_b32_e32 v21, v44
	v_mov_b32_e32 v22, v42
	v_mov_b32_e32 v23, v45
	v_pk_add_f32 v[20:21], v[20:21], v[22:23]
	v_add_f32_e32 v0, v18, v19
	v_pk_add_f32 v[20:21], v[20:21], v[20:21] op_sel:[0,1] op_sel_hi:[1,0]
	v_add_f32_e32 v18, 0, v0
	s_waitcnt lgkmcnt(3)
	v_add_f32_e32 v22, v38, v39
	v_add_f32_e32 v24, v40, v41
	s_waitcnt lgkmcnt(2)
	v_mov_b32_e32 v19, v34
	v_mov_b32_e32 v21, v35
	v_mov_b32_e32 v23, v36
	v_mov_b32_e32 v25, v37
	v_pk_add_f32 v[18:19], v[18:19], v[20:21]
	v_pk_add_f32 v[20:21], v[22:23], v[24:25]
	s_waitcnt lgkmcnt(0)
	v_mov_b32_e32 v136, v27
	v_pk_add_f32 v[18:19], v[18:19], v[20:21]
	v_mov_b32_e32 v137, v28
	v_add_f32_e32 v0, v18, v19
	v_mov_b32_e32 v204, v0
	s_nop 1
	v_add_f32_dpp v204, v204, v204 quad_perm:[1,0,3,2] row_mask:0xf bank_mask:0xf
	s_nop 1
	v_add_f32_dpp v204, v204, v204 quad_perm:[2,3,0,1] row_mask:0xf bank_mask:0xf
	s_nop 1
	v_add_f32_dpp v204, v204, v204 row_ror:4 row_mask:0xf bank_mask:0xf
	s_nop 1
	v_add_f32_dpp v204, v204, v204 row_ror:8 row_mask:0xf bank_mask:0xf
	s_nop 1
	v_add_f32_dpp v204, v204, v204 row_bcast:15 row_mask:0xa bank_mask:0xf
	s_nop 1
	v_add_f32_dpp v204, v204, v204 row_bcast:31 row_mask:0xc bank_mask:0xf
	s_nop 1
	v_readlane_b32 s98, v204, 63
	v_mov_b32_e32 v138, v26
	v_mov_b32_e32 v139, v29
	v_pk_add_f32 v[136:137], v[136:137], v[138:139]
	s_mov_b32 s0, 0x3a800000
	v_pk_add_f32 v[136:137], v[136:137], v[136:137] op_sel:[0,1] op_sel_hi:[1,0]
	s_mov_b32 s50, 0x800000
	s_add_i32 s94, s94, s96
	s_mov_b32 s70, s96
	s_mov_b32 s84, s97
	s_waitcnt lgkmcnt(0)
	s_nop 1
	v_mov_b32_e32 v133, s98
	v_fmamk_f32 v121, v133, 0xba800000, v47
	v_fmamk_f32 v120, v133, 0xba800000, v46
	v_fmamk_f32 v49, v133, 0xba800000, v49
	v_fmac_f32_e32 v48, 0xba800000, v133
	v_pk_mul_f32 v[18:19], v[48:49], v[48:49]
	v_pk_mul_f32 v[20:21], v[120:121], v[120:121]
	v_fmamk_f32 v47, v133, 0xba800000, v43
	v_pk_mov_b32 v[22:23], v[20:21], v[18:19] op_sel:[1,0]
	v_mov_b32_e32 v21, v19
	v_pk_add_f32 v[18:19], v[22:23], v[20:21]
	v_mov_b32_e32 v20, v30
	v_pk_add_f32 v[134:135], v[18:19], v[18:19] op_sel_hi:[0,1]
	v_mov_b32_e32 v18, v31
	v_mov_b32_e32 v19, v32
	v_mov_b32_e32 v21, v33
	v_pk_add_f32 v[18:19], v[18:19], v[20:21]
	ds_read_b128 v[22:25], v132 offset:2048
	v_add_f32_e32 v0, v18, v19
	ds_read_b128 v[18:21], v132 offset:3072
	v_add_f32_e32 v118, 0, v0
	v_fmamk_f32 v46, v133, 0xba800000, v42
	s_waitcnt lgkmcnt(1)
	v_add_f32_e32 v138, v22, v23
	v_add_f32_e32 v140, v24, v25
	s_waitcnt lgkmcnt(0)
	v_mov_b32_e32 v119, v18
	v_mov_b32_e32 v137, v19
	v_mov_b32_e32 v139, v20
	v_mov_b32_e32 v141, v21
	v_pk_add_f32 v[118:119], v[118:119], v[136:137]
	v_pk_add_f32 v[136:137], v[138:139], v[140:141]
	v_fmamk_f32 v45, v133, 0xba800000, v45
	v_pk_add_f32 v[118:119], v[118:119], v[136:137]
	v_fmac_f32_e32 v44, 0xba800000, v133
	v_add_f32_e32 v0, v118, v119
	v_mov_b32_e32 v204, v0
	s_nop 1
	v_add_f32_dpp v204, v204, v204 quad_perm:[1,0,3,2] row_mask:0xf bank_mask:0xf
	s_nop 1
	v_add_f32_dpp v204, v204, v204 quad_perm:[2,3,0,1] row_mask:0xf bank_mask:0xf
	s_nop 1
	v_add_f32_dpp v204, v204, v204 row_ror:4 row_mask:0xf bank_mask:0xf
	s_nop 1
	v_add_f32_dpp v204, v204, v204 row_ror:8 row_mask:0xf bank_mask:0xf
	s_nop 1
	v_add_f32_dpp v204, v204, v204 row_bcast:15 row_mask:0xa bank_mask:0xf
	s_nop 1
	v_add_f32_dpp v204, v204, v204 row_bcast:31 row_mask:0xc bank_mask:0xf
	s_nop 1
	v_readlane_b32 s98, v204, 63
	v_pk_mul_f32 v[42:43], v[44:45], v[44:45]
	v_pk_mul_f32 v[118:119], v[46:47], v[46:47]
	v_fmac_f32_e32 v40, 0xba800000, v133
	v_pk_mov_b32 v[136:137], v[118:119], v[42:43] op_sel:[1,0]
	v_mov_b32_e32 v119, v43
	v_pk_add_f32 v[42:43], v[136:137], v[118:119]
	v_fmamk_f32 v118, v133, 0xba800000, v38
	v_pk_add_f32 v[42:43], v[42:43], v[42:43] op_sel_hi:[0,1]
	v_fmamk_f32 v119, v133, 0xba800000, v39
	v_mul_f32_e32 v0, v118, v118
	v_pk_fma_f32 v[38:39], v[118:119], v[118:119], v[0:1] op_sel_hi:[1,1,0]
	v_fmamk_f32 v41, v133, 0xba800000, v41
	v_mul_f32_e32 v0, v40, v40
	v_pk_fma_f32 v[136:137], v[40:41], v[40:41], v[0:1] op_sel_hi:[1,1,0]
	v_fmamk_f32 v37, v133, 0xba800000, v37
	v_fmamk_f32 v36, v133, 0xba800000, v36
	v_fmamk_f32 v35, v133, 0xba800000, v35
	v_fmac_f32_e32 v34, 0xba800000, v133
	v_mul_f32_e32 v38, v34, v34
	v_mul_f32_e32 v136, v35, v35
	v_mul_f32_e32 v134, v36, v36
	v_mul_f32_e32 v42, v37, v37
	v_pk_add_f32 v[38:39], v[38:39], v[136:137]
	v_pk_add_f32 v[42:43], v[134:135], v[42:43]
	s_waitcnt lgkmcnt(0)
	s_nop 1
	v_mov_b32_e32 v133, s98
	v_fmamk_f32 v31, v133, 0xba800000, v31
	v_fmamk_f32 v30, v133, 0xba800000, v30
	v_fmamk_f32 v33, v133, 0xba800000, v33
	v_fmac_f32_e32 v32, 0xba800000, v133
	v_pk_add_f32 v[38:39], v[38:39], v[42:43]
	v_pk_mul_f32 v[42:43], v[32:33], v[32:33]
	v_pk_mul_f32 v[134:135], v[30:31], v[30:31]
	v_fmamk_f32 v27, v133, 0xba800000, v27
	v_pk_mov_b32 v[136:137], v[134:135], v[42:43] op_sel:[1,0]
	v_mov_b32_e32 v135, v43
	v_fmamk_f32 v26, v133, 0xba800000, v26
	v_fmamk_f32 v29, v133, 0xba800000, v29
	v_fmac_f32_e32 v28, 0xba800000, v133
	v_pk_add_f32 v[42:43], v[136:137], v[134:135]
	v_pk_mul_f32 v[134:135], v[28:29], v[28:29]
	v_pk_mul_f32 v[136:137], v[26:27], v[26:27]
	v_fmamk_f32 v22, v133, 0xba800000, v22
	v_pk_mov_b32 v[138:139], v[136:137], v[134:135] op_sel:[1,0]
	v_mov_b32_e32 v137, v135
	v_fmamk_f32 v23, v133, 0xba800000, v23
	v_fmac_f32_e32 v24, 0xba800000, v133
	v_mul_f32_e32 v0, v22, v22
	v_pk_add_f32 v[134:135], v[138:139], v[136:137]
	v_fmamk_f32 v25, v133, 0xba800000, v25
	v_pk_fma_f32 v[136:137], v[22:23], v[22:23], v[0:1] op_sel_hi:[1,1,0]
	v_mul_f32_e32 v0, v24, v24
	v_pk_add_f32 v[42:43], v[42:43], v[42:43] op_sel_hi:[0,1]
	v_pk_add_f32 v[134:135], v[134:135], v[134:135] op_sel_hi:[0,1]
	v_pk_fma_f32 v[138:139], v[24:25], v[24:25], v[0:1] op_sel_hi:[1,1,0]
	v_fmamk_f32 v21, v133, 0xba800000, v21
	v_fmamk_f32 v20, v133, 0xba800000, v20
	v_fmamk_f32 v19, v133, 0xba800000, v19
	v_fmac_f32_e32 v18, 0xba800000, v133
	v_mul_f32_e32 v136, v18, v18
	v_mul_f32_e32 v138, v19, v19
	v_mul_f32_e32 v42, v20, v20
	v_mul_f32_e32 v134, v21, v21
	v_pk_add_f32 v[136:137], v[136:137], v[138:139]
	v_pk_add_f32 v[42:43], v[42:43], v[134:135]
	v_mov_b32_e32 v135, v38
	v_pk_add_f32 v[42:43], v[136:137], v[42:43]
	s_nop 0
	v_mov_b32_e32 v134, v42
	v_mov_b32_e32 v38, v43
	v_pk_add_f32 v[38:39], v[134:135], v[38:39]
	v_mov_b32_e32 v204, v38
	v_mov_b32_e32 v205, v39
	s_nop 1
	v_add_f32_dpp v204, v204, v204 quad_perm:[1,0,3,2] row_mask:0xf bank_mask:0xf
	v_add_f32_dpp v205, v205, v205 quad_perm:[1,0,3,2] row_mask:0xf bank_mask:0xf
	s_nop 1
	v_add_f32_dpp v204, v204, v204 quad_perm:[2,3,0,1] row_mask:0xf bank_mask:0xf
	v_add_f32_dpp v205, v205, v205 quad_perm:[2,3,0,1] row_mask:0xf bank_mask:0xf
	s_nop 1
	v_add_f32_dpp v204, v204, v204 row_ror:4 row_mask:0xf bank_mask:0xf
	v_add_f32_dpp v205, v205, v205 row_ror:4 row_mask:0xf bank_mask:0xf
	s_nop 1
	v_add_f32_dpp v204, v204, v204 row_ror:8 row_mask:0xf bank_mask:0xf
	v_add_f32_dpp v205, v205, v205 row_ror:8 row_mask:0xf bank_mask:0xf
	s_nop 1
	v_add_f32_dpp v204, v204, v204 row_bcast:15 row_mask:0xa bank_mask:0xf
	v_add_f32_dpp v205, v205, v205 row_bcast:15 row_mask:0xa bank_mask:0xf
	s_nop 1
	v_add_f32_dpp v204, v204, v204 row_bcast:31 row_mask:0xc bank_mask:0xf
	v_add_f32_dpp v205, v205, v205 row_bcast:31 row_mask:0xc bank_mask:0xf
	s_nop 1
	v_readlane_b32 s98, v204, 63
	v_readlane_b32 s99, v205, 63
	v_add_u32_e32 v134, s2, v123
	v_ashrrev_i32_e32 v135, 31, v134
	v_lshlrev_b64 v[134:135], 11, v[134:135]
	s_waitcnt lgkmcnt(0)
	s_nop 1
	v_mov_b32_e32 v38, s98
	v_mov_b32_e32 v39, s99
	s_nop 0
	v_pk_fma_f32 v[38:39], v[38:39], s[0:1], v[150:151] op_sel_hi:[1,0,0]
	s_nop 0
	v_mul_f32_e32 v0, 0x4b800000, v39
	v_cmp_gt_f32_e32 vcc, s50, v39
	s_nop 1
	v_cndmask_b32_e32 v0, v39, v0, vcc
	v_rsq_f32_e32 v0, v0
	s_nop 0
	v_mul_f32_e32 v39, 0x45800000, v0
	v_cndmask_b32_e32 v0, v0, v39, vcc
	v_pk_mul_f32 v[42:43], v[120:121], v[0:1] op_sel_hi:[1,0]
	v_pk_mul_f32 v[48:49], v[48:49], v[0:1] op_sel_hi:[1,0]
	v_pk_mul_f32 v[120:121], v[2:3], v[42:43]
	v_pk_mul_f32 v[48:49], v[4:5], v[48:49]
	v_mul_f32_e32 v39, 0xbfb8aa3b, v120
	v_exp_f32_e32 v42, v39
	v_mul_f32_e32 v39, 0xbfb8aa3b, v121
	v_exp_f32_e32 v43, v39
	v_pk_mul_f32 v[46:47], v[46:47], v[0:1] op_sel_hi:[1,0]
	v_pk_mul_f32 v[44:45], v[44:45], v[0:1] op_sel_hi:[1,0]
	v_pk_mul_f32 v[46:47], v[6:7], v[46:47]
	v_pk_add_f32 v[136:137], v[42:43], 1.0 op_sel_hi:[1,0]
	v_lshl_add_u64 v[42:43], v[116:117], 0, v[134:135]
	v_pk_mul_f32 v[44:45], v[8:9], v[44:45]
	v_pk_mul_f32 v[40:41], v[40:41], v[0:1] op_sel_hi:[1,0]
	v_pk_mul_f32 v[34:35], v[34:35], v[0:1] op_sel_hi:[1,0]
	v_mul_f32_e32 v134, 0xbfb8aa3b, v48
	v_mul_f32_e32 v135, 0xbfb8aa3b, v49
	v_exp_f32_e32 v134, v134
	v_exp_f32_e32 v135, v135
	v_rcp_f32_e32 v39, v137
	s_nop 0
	v_mul_f32_e32 v39, v121, v39
	v_pk_add_f32 v[134:135], v[134:135], 1.0 op_sel_hi:[1,0]
	v_rcp_f32_e32 v121, v136
	s_nop 0
	v_mul_f32_e32 v133, v120, v121
	v_pk_mul_f32 v[40:41], v[12:13], v[40:41]
	v_rcp_f32_e32 v120, v135
	s_nop 0
	v_mul_f32_e32 v49, v49, v120
	v_pk_mul_f32 v[34:35], v[14:15], v[34:35]
	v_mul_f32_e32 v120, 0xbfb8aa3b, v46
	v_mul_f32_e32 v121, 0xbfb8aa3b, v47
	v_exp_f32_e32 v120, v120
	v_exp_f32_e32 v121, v121
	v_rcp_f32_e32 v135, v134
	s_nop 0
	v_mul_f32_e32 v134, v48, v135
	v_cvt_pk_bf16_f32 v48, v133, v39
	v_cvt_pk_bf16_f32 v49, v134, v49
	v_pk_add_f32 v[120:121], v[120:121], 1.0 op_sel_hi:[1,0]
	global_store_dwordx2 v[42:43], v[48:49], off
	v_pk_mul_f32 v[36:37], v[36:37], v[0:1] op_sel_hi:[1,0]
	v_mul_f32_e32 v48, 0xbfb8aa3b, v44
	v_mul_f32_e32 v49, 0xbfb8aa3b, v45
	v_exp_f32_e32 v48, v48
	v_exp_f32_e32 v49, v49
	v_rcp_f32_e32 v39, v121
	s_nop 0
	v_mul_f32_e32 v39, v47, v39
	v_pk_add_f32 v[48:49], v[48:49], 1.0 op_sel_hi:[1,0]
	v_rcp_f32_e32 v47, v120
	s_nop 0
	v_mul_f32_e32 v120, v46, v47
	v_pk_mul_f32 v[36:37], v[16:17], v[36:37]
	v_rcp_f32_e32 v46, v49
	s_nop 0
	v_mul_f32_e32 v45, v45, v46
	v_pk_mul_f32 v[46:47], v[118:119], v[0:1] op_sel_hi:[1,0]
	v_rcp_f32_e32 v49, v48
	s_nop 0
	v_mul_f32_e32 v48, v44, v49
	v_pk_mul_f32 v[46:47], v[10:11], v[46:47]
	v_cvt_pk_bf16_f32 v45, v48, v45
	v_mul_f32_e32 v118, 0xbfb8aa3b, v46
	v_mul_f32_e32 v119, 0xbfb8aa3b, v47
	v_exp_f32_e32 v118, v118
	v_exp_f32_e32 v119, v119
	v_cvt_pk_bf16_f32 v44, v120, v39
	global_store_dwordx2 v[42:43], v[44:45], off offset:512
	v_pk_add_f32 v[48:49], v[118:119], 1.0 op_sel_hi:[1,0]
	s_nop 0
	s_nop 0
	v_mul_f32_e32 v45, 0xbfb8aa3b, v41
	v_mul_f32_e32 v44, 0xbfb8aa3b, v40
	v_exp_f32_e32 v44, v44
	v_exp_f32_e32 v45, v45
	v_rcp_f32_e32 v39, v49
	s_nop 0
	v_mul_f32_e32 v39, v47, v39
	v_pk_add_f32 v[44:45], v[44:45], 1.0 op_sel_hi:[1,0]
	v_rcp_f32_e32 v47, v48
	s_nop 0
	v_mul_f32_e32 v48, v46, v47
	v_rcp_f32_e32 v46, v45
	s_nop 0
	v_mul_f32_e32 v41, v41, v46
	v_mul_f32_e32 v46, 0xbfb8aa3b, v34
	v_mul_f32_e32 v47, 0xbfb8aa3b, v35
	v_exp_f32_e32 v46, v46
	v_exp_f32_e32 v47, v47
	v_rcp_f32_e32 v45, v44
	s_nop 0
	v_mul_f32_e32 v44, v40, v45
	v_cvt_pk_bf16_f32 v41, v44, v41
	v_cvt_pk_bf16_f32 v40, v48, v39
	v_pk_add_f32 v[44:45], v[46:47], 1.0 op_sel_hi:[1,0]
	global_store_dwordx2 v[42:43], v[40:41], off offset:1024
	s_nop 0
	v_mul_f32_e32 v40, 0xbfb8aa3b, v36
	v_mul_f32_e32 v41, 0xbfb8aa3b, v37
	v_rcp_f32_e32 v0, v45
	s_nop 0
	v_mul_f32_e32 v0, v35, v0
	v_exp_f32_e32 v40, v40
	v_exp_f32_e32 v41, v41
	s_nop 0
	v_pk_add_f32 v[40:41], v[40:41], 1.0 op_sel_hi:[1,0]
	v_rcp_f32_e32 v35, v44
	s_nop 0
	v_mul_f32_e32 v34, v34, v35
	v_cvt_pk_bf16_f32 v34, v34, v0
	v_rcp_f32_e32 v35, v41
	s_nop 0
	v_mul_f32_e32 v35, v37, v35
	v_rcp_f32_e32 v37, v40
	s_nop 0
	v_mul_f32_e32 v36, v36, v37
	v_mul_f32_e32 v37, 0x4b800000, v38
	v_cmp_gt_f32_e32 vcc, s50, v38
	v_cvt_pk_bf16_f32 v35, v36, v35
	global_store_dwordx2 v[42:43], v[34:35], off offset:1536
	v_cndmask_b32_e32 v37, v38, v37, vcc
	v_rsq_f32_e32 v37, v37
	v_add_u32_e32 v36, s2, v130
	s_add_i32 s2, s2, s97
	v_mul_f32_e32 v0, 0x45800000, v37
	v_cndmask_b32_e32 v0, v37, v0, vcc
	v_pk_mul_f32 v[30:31], v[30:31], v[0:1] op_sel_hi:[1,0]
	v_ashrrev_i32_e32 v37, 31, v36
	v_pk_mul_f32 v[34:35], v[2:3], v[30:31]
	v_lshlrev_b64 v[36:37], 11, v[36:37]
	v_mul_f32_e32 v30, 0xbfb8aa3b, v34
	v_mul_f32_e32 v31, 0xbfb8aa3b, v35
	v_exp_f32_e32 v30, v30
	v_exp_f32_e32 v31, v31
	v_pk_mul_f32 v[32:33], v[32:33], v[0:1] op_sel_hi:[1,0]
	v_pk_mul_f32 v[26:27], v[26:27], v[0:1] op_sel_hi:[1,0]
	v_pk_mul_f32 v[32:33], v[4:5], v[32:33]
	v_pk_add_f32 v[38:39], v[30:31], 1.0 op_sel_hi:[1,0]
	v_lshl_add_u64 v[30:31], v[116:117], 0, v[36:37]
	v_pk_mul_f32 v[26:27], v[6:7], v[26:27]
	v_pk_mul_f32 v[28:29], v[28:29], v[0:1] op_sel_hi:[1,0]
	v_pk_mul_f32 v[22:23], v[22:23], v[0:1] op_sel_hi:[1,0]
	v_rcp_f32_e32 v36, v39
	s_nop 0
	v_mul_f32_e32 v39, v35, v36
	v_mul_f32_e32 v36, 0xbfb8aa3b, v32
	v_mul_f32_e32 v37, 0xbfb8aa3b, v33
	v_exp_f32_e32 v36, v36
	v_exp_f32_e32 v37, v37
	s_nop 0
	v_pk_add_f32 v[36:37], v[36:37], 1.0 op_sel_hi:[1,0]
	v_rcp_f32_e32 v35, v38
	s_nop 0
	v_mul_f32_e32 v38, v34, v35
	v_pk_mul_f32 v[28:29], v[8:9], v[28:29]
	v_rcp_f32_e32 v34, v37
	s_nop 0
	v_mul_f32_e32 v33, v33, v34
	v_pk_mul_f32 v[22:23], v[10:11], v[22:23]
	v_mul_f32_e32 v34, 0xbfb8aa3b, v26
	v_mul_f32_e32 v35, 0xbfb8aa3b, v27
	v_exp_f32_e32 v34, v34
	v_exp_f32_e32 v35, v35
	v_rcp_f32_e32 v37, v36
	s_nop 0
	v_mul_f32_e32 v36, v32, v37
	v_cvt_pk_bf16_f32 v33, v36, v33
	v_cvt_pk_bf16_f32 v32, v38, v39
	v_pk_add_f32 v[34:35], v[34:35], 1.0 op_sel_hi:[1,0]
	global_store_dwordx2 v[30:31], v[32:33], off
	v_pk_mul_f32 v[24:25], v[24:25], v[0:1] op_sel_hi:[1,0]
	v_pk_mul_f32 v[18:19], v[18:19], v[0:1] op_sel_hi:[1,0]
	v_pk_mul_f32 v[24:25], v[12:13], v[24:25]
	v_rcp_f32_e32 v32, v35
	s_nop 0
	v_mul_f32_e32 v35, v27, v32
	v_mul_f32_e32 v32, 0xbfb8aa3b, v28
	v_mul_f32_e32 v33, 0xbfb8aa3b, v29
	v_exp_f32_e32 v32, v32
	v_exp_f32_e32 v33, v33
	s_nop 0
	v_pk_add_f32 v[32:33], v[32:33], 1.0 op_sel_hi:[1,0]
	v_rcp_f32_e32 v27, v34
	s_nop 0
	v_mul_f32_e32 v34, v26, v27
	v_pk_mul_f32 v[18:19], v[14:15], v[18:19]
	v_rcp_f32_e32 v26, v33
	s_nop 0
	v_mul_f32_e32 v29, v29, v26
	v_pk_mul_f32 v[20:21], v[20:21], v[0:1] op_sel_hi:[1,0]
	v_mul_f32_e32 v26, 0xbfb8aa3b, v22
	v_mul_f32_e32 v27, 0xbfb8aa3b, v23
	v_exp_f32_e32 v26, v26
	v_exp_f32_e32 v27, v27
	v_rcp_f32_e32 v33, v32
	s_nop 0
	v_mul_f32_e32 v32, v28, v33
	v_cvt_pk_bf16_f32 v29, v32, v29
	v_cvt_pk_bf16_f32 v28, v34, v35
	v_pk_add_f32 v[26:27], v[26:27], 1.0 op_sel_hi:[1,0]
	global_store_dwordx2 v[30:31], v[28:29], off offset:512
	v_pk_mul_f32 v[20:21], v[16:17], v[20:21]
	v_rcp_f32_e32 v28, v27
	s_nop 0
	v_mul_f32_e32 v27, v23, v28
	v_mul_f32_e32 v28, 0xbfb8aa3b, v24
	v_mul_f32_e32 v29, 0xbfb8aa3b, v25
	v_exp_f32_e32 v28, v28
	v_exp_f32_e32 v29, v29
	s_nop 0
	v_pk_add_f32 v[28:29], v[28:29], 1.0 op_sel_hi:[1,0]
	v_rcp_f32_e32 v23, v26
	s_nop 0
	v_mul_f32_e32 v26, v22, v23
	v_rcp_f32_e32 v22, v29
	s_nop 0
	v_mul_f32_e32 v25, v25, v22
	v_mul_f32_e32 v22, 0xbfb8aa3b, v18
	v_mul_f32_e32 v23, 0xbfb8aa3b, v19
	v_exp_f32_e32 v22, v22
	v_exp_f32_e32 v23, v23
	v_rcp_f32_e32 v29, v28
	s_nop 0
	v_mul_f32_e32 v28, v24, v29
	v_cvt_pk_bf16_f32 v24, v26, v27
	v_cvt_pk_bf16_f32 v25, v28, v25
	v_pk_add_f32 v[22:23], v[22:23], 1.0 op_sel_hi:[1,0]
	global_store_dwordx2 v[30:31], v[24:25], off offset:1024
	s_nop 0
	v_mul_f32_e32 v24, 0xbfb8aa3b, v20
	v_mul_f32_e32 v25, 0xbfb8aa3b, v21
	v_rcp_f32_e32 v0, v23
	s_nop 0
	v_mul_f32_e32 v0, v19, v0
	v_exp_f32_e32 v24, v24
	v_exp_f32_e32 v25, v25
	s_nop 0
	v_pk_add_f32 v[24:25], v[24:25], 1.0 op_sel_hi:[1,0]
	v_rcp_f32_e32 v19, v22
	s_nop 0
	v_mul_f32_e32 v18, v18, v19
	v_cvt_pk_bf16_f32 v18, v18, v0
	v_rcp_f32_e32 v19, v25
	s_nop 0
	v_mul_f32_e32 v19, v21, v19
	v_readlane_b32 s0, v254, 23
	v_rcp_f32_e32 v21, v24
	s_nop 0
	v_mul_f32_e32 v20, v20, v21
	v_cvt_pk_bf16_f32 v19, v20, v19
	s_cmp_ge_i32 s94, s0
	global_store_dwordx2 v[30:31], v[18:19], off offset:1536
	s_barrier
	s_cbranch_scc0 .LBB0_501
	v_readlane_b32 s96, v253, 54
	v_readlane_b32 s18, v253, 51
	v_readlane_b32 s76, v255, 7
	v_readlane_b32 s88, v253, 53
	v_readlane_b32 s97, v253, 55
	v_readlane_b32 s69, v253, 56
	v_readlane_b32 s72, v253, 57
	v_readlane_b32 s74, v253, 59
	s_movk_i32 s71, 0x200
	v_readlane_b32 s75, v253, 60
	v_readlane_b32 s78, v253, 61
	v_readlane_b32 s79, v253, 62
	v_readlane_b32 s80, v253, 63
	v_readlane_b32 s81, v254, 0
	v_readlane_b32 s82, v254, 1
	v_readlane_b32 s83, v254, 2
	s_movk_i32 s85, 0x400
	s_movk_i32 s87, 0x3000
	v_readlane_b32 s89, v254, 3
	v_readlane_b32 s48, v253, 49
	s_movk_i32 s49, 0x3fff
	s_movk_i32 s51, 0x40ff
	s_mov_b32 s52, 0x2aaaaaab
	s_movk_i32 s53, 0x80
	s_movk_i32 s54, 0x7ff
	s_movk_i32 s55, 0xfff
	s_movk_i32 s56, 0x3ff
	s_movk_i32 s57, 0xfa00
	s_movk_i32 s58, 0x1800
	s_movk_i32 s59, 0x500
	s_movk_i32 s60, 0xff00
	s_movk_i32 s61, 0x2ff
	s_movk_i32 s62, 0x1ff
	s_movk_i32 s63, 0x67
	s_movk_i32 s64, 0x6f
	s_movk_i32 s27, 0x77
	s_movk_i32 s29, 0x7f
	v_readlane_b32 s30, v253, 50
	s_mov_b32 s31, 0x3f2aaaab
	s_mov_b32 s43, 0x3f317218
	s_mov_b32 s44, 0x7f800000
	s_mov_b32 s45, 0x33800000
	s_movk_i32 s47, 0x210
	s_movk_i32 s46, 0x1000
	s_mov_b32 s65, 0x16900000
	s_movk_i32 s66, 0x110
	s_movk_i32 s28, 0x2000
	s_mov_b32 s34, 0x2e8ba2e9
	s_movk_i32 s35, 0xea00
	s_movk_i32 s36, 0xd400
	s_movk_i32 s37, 0xaff
	s_mov_b32 s38, 0x7fffea10
	s_mov_b32 s39, 0x7fffea20
	s_mov_b32 s40, 0x7fffea30
	s_mov_b32 s41, 0xffd40000
	s_movk_i32 s42, 0x57f
	v_readlane_b32 s19, v253, 52
	v_readlane_b32 s25, v254, 63
	v_readlane_b32 s26, v255, 9
	v_readlane_b32 s77, v255, 8
	v_readlane_b32 s68, v255, 6
	v_readlane_b32 s73, v253, 58
